# cache policy: nt also on ROW1's read-once row loads and on the router's H32 operand DMA
# speedup vs baseline: 1.0223x; 1.0026x over previous
; __device__ __forceinline__ f32x4 bf4(u32x2 q) { return (f32x4){__uint_as_float(q.x << 16), __uint_as_float(q.x & 0xffff0000u), __uint_as_float(q.y << 16), __uint_as_float(q.y & 0xffff0000u)}; }
; __device__ __forceinline__ void phase_row1(const Frame& F, int l) {
;     ...
;         __syncthreads();
;         if (F.tid < 64) lc[F.tid] = 0;
;         const bf16* XB = (const bf16*)(F.ws + WS_XB);
;         f32x4 g1[4], vlg[4], vlb[4], sc1[4], sh[4];
;         { const float* modp = MOD + ((size_t)l * 8 + ((chunk * 64) >> 11)) * 6144;
;           load_row(modp + 2048, lane, g1); load_row(F.in[12] + (l * 2 + 0) * D, lane, vlg); load_row(F.in[13] + (l * 2 + 0) * D, lane, vlb); load_row(modp + 3 * 1024, lane, sh); load_row(modp + 4 * 1024, lane, sc1);
; #pragma unroll
;           for (int j = 0; j < 4; ++j) { g1[j] = g1[j] + 1.f; sc1[j] = sc1[j] + 1.f; } }
;         f32x4 cx[4], nx[4]; u32x2 cy[4], ny[4];
;         { const int row = chunk * 64 + w * 8; if (l == 0) load_row(F.in[0] + (size_t)row * D, lane, cx); else load_row_bf16(XB + (size_t)row * D, lane, cx);
; #pragma unroll
;           for (int j = 0; j < 4; ++j) cy[j] = *(const u32x2*)((const bf16*)(F.ws + WS_MIX) + (size_t)row * D + 256 * j + 4 * lane); }
;         for (int i = 0; i < 8; ++i) {
;             const int row = chunk * 64 + w * 8 + i, b = row >> 11;
;             const float* modp = MOD + ((size_t)l * 8 + b) * 6144;
;             if (i + 1 < 8) { if (l == 0) load_row(F.in[0] + (size_t)(row + 1) * D, lane, nx); else load_row_bf16(XB + (size_t)(row + 1) * D, lane, nx);
; #pragma unroll
;                 for (int j = 0; j < 4; ++j) ny[j] = *(const u32x2*)((const bf16*)(F.ws + WS_MIX) + (size_t)(row + 1) * D + 256 * j + 4 * lane); }
;             f32x4 x[4], y[4];
; #pragma unroll
;             for (int j = 0; j < 4; ++j) { x[j] = cx[j]; y[j] = bf4(cy[j]); }
.LBB0_2135:
	s_waitcnt lgkmcnt(0)
	s_barrier
	s_and_saveexec_b64 s[4:5], s[42:43]
	ds_write_b32 v156, v199 offset:16384
	s_or_b64 exec, exec, s[4:5]
	s_ashr_i32 s3, s34, 5
	s_ashr_i32 s4, s3, 31
	s_add_u32 s3, s14, s3
	s_addc_u32 s4, s15, s4
	s_mulk_i32 s4, 0x6000
	s_mul_hi_u32 s5, s3, 0x6000
	s_add_i32 s5, s5, s4
	s_mulk_i32 s3, 0x6000
	s_add_u32 s4, s8, s3
	s_addc_u32 s5, s9, s5
	v_lshl_add_u64 v[66:67], s[4:5], 0, v[198:199]
	s_mov_b64 s[4:5], 0x2000
	v_add_co_u32_e32 v20, vcc, s70, v66
	v_lshl_add_u64 v[18:19], v[66:67], 0, s[4:5]
	s_nop 0
	v_addc_co_u32_e32 v21, vcc, 0, v67, vcc
	global_load_dwordx4 v[90:93], v[18:19], off offset:1024
	global_load_dwordx4 v[86:89], v[18:19], off offset:2048
	global_load_dwordx4 v[94:97], v[20:21], off
	global_load_dwordx4 v[82:85], v[18:19], off offset:3072
	s_nop 0
	global_load_dwordx4 v[18:21], v[124:125], off
	global_load_dwordx4 v[22:25], v[124:125], off offset:1024
	global_load_dwordx4 v[26:29], v[124:125], off offset:2048
	global_load_dwordx4 v[30:33], v[124:125], off offset:3072
	global_load_dwordx4 v[34:37], v[126:127], off
	global_load_dwordx4 v[38:41], v[126:127], off offset:1024
	global_load_dwordx4 v[42:45], v[126:127], off offset:2048
	global_load_dwordx4 v[46:49], v[126:127], off offset:3072
	v_add_co_u32_e32 v58, vcc, 0x3000, v66
	s_mov_b64 s[4:5], 0x3000
	s_nop 0
	v_addc_co_u32_e32 v59, vcc, 0, v67, vcc
	v_lshl_add_u64 v[62:63], v[66:67], 0, s[4:5]
	v_lshl_add_u64 v[68:69], v[66:67], 0, s[24:25]
	v_add_co_u32_e32 v66, vcc, 0x4000, v66
	global_load_dwordx4 v[50:53], v[62:63], off offset:1024
	global_load_dwordx4 v[54:57], v[62:63], off offset:2048
	s_nop 0
	global_load_dwordx4 v[58:61], v[58:59], off
	s_nop 0
	global_load_dwordx4 v[62:65], v[62:63], off offset:3072
	v_addc_co_u32_e32 v67, vcc, 0, v67, vcc
	global_load_dwordx4 v[106:109], v[68:69], off offset:1024
	global_load_dwordx4 v[102:105], v[68:69], off offset:2048
	global_load_dwordx4 v[110:113], v[66:67], off
	global_load_dwordx4 v[98:101], v[68:69], off offset:3072
	s_lshl_b32 s3, s34, 6
	s_add_i32 s44, s3, s10
	s_ashr_i32 s45, s44, 31
	s_and_b64 vcc, exec, s[28:29]
	s_cbranch_vccz .LBB0_2156
	s_lshl_b64 s[26:27], s[44:45], 11
	v_lshl_add_u64 v[66:67], v[116:117], 0, s[26:27]
	global_load_dwordx2 v[68:69], v[66:67], off nt
	global_load_dwordx2 v[70:71], v[66:67], off offset:512 nt
	global_load_dwordx2 v[72:73], v[66:67], off offset:1024 nt
	global_load_dwordx2 v[146:147], v[66:67], off offset:1536 nt
	s_waitcnt vmcnt(3)
	v_lshlrev_b32_e32 v78, 16, v68
	v_and_b32_e32 v79, 0xffff0000, v68
	v_lshlrev_b32_e32 v80, 16, v69
	v_and_b32_e32 v81, 0xffff0000, v69
	s_waitcnt vmcnt(2)
	v_lshlrev_b32_e32 v74, 16, v70
	v_and_b32_e32 v75, 0xffff0000, v70
	v_lshlrev_b32_e32 v76, 16, v71
	v_and_b32_e32 v77, 0xffff0000, v71
	s_waitcnt vmcnt(1)
	v_lshlrev_b32_e32 v70, 16, v72
	v_and_b32_e32 v71, 0xffff0000, v72
	v_lshlrev_b32_e32 v72, 16, v73
	v_and_b32_e32 v73, 0xffff0000, v73
	s_waitcnt vmcnt(0)
	v_lshlrev_b32_e32 v66, 16, v146
	v_and_b32_e32 v67, 0xffff0000, v146
	v_lshlrev_b32_e32 v68, 16, v147
	v_and_b32_e32 v69, 0xffff0000, v147
	s_cbranch_execnz .LBB0_2140
.LBB0_2139:
	s_lshl_b64 s[4:5], s[44:45], 12
	v_lshl_add_u64 v[66:67], v[128:129], 0, s[4:5]
	global_load_dwordx4 v[78:81], v[66:67], off nt
	global_load_dwordx4 v[74:77], v[66:67], off offset:1024 nt
	global_load_dwordx4 v[70:73], v[66:67], off offset:2048 nt
	s_nop 0
	global_load_dwordx4 v[66:69], v[66:67], off offset:3072 nt
	s_lshl_b64 s[26:27], s[44:45], 11
.LBB0_2140:
	v_lshl_add_u64 v[146:147], v[118:119], 0, s[26:27]
	global_load_dwordx2 v[152:153], v[146:147], off nt
	global_load_dwordx2 v[150:151], v[146:147], off offset:512 nt
	global_load_dwordx2 v[148:149], v[146:147], off offset:1024 nt
	s_nop 0
	global_load_dwordx2 v[146:147], v[146:147], off offset:1536 nt
	v_and_b32_e32 v158, 64, v225
	v_add_u32_e32 v163, 64, v158
	v_xor_b32_e32 v135, 32, v225
	v_cmp_lt_i32_e32 vcc, v135, v163
	v_xor_b32_e32 v159, 16, v225
	v_xor_b32_e32 v160, 8, v225
	v_cndmask_b32_e32 v135, v225, v135, vcc
	v_cmp_lt_i32_e32 vcc, v159, v163
	v_xor_b32_e32 v161, 4, v225
	v_xor_b32_e32 v162, 2, v225
	v_cndmask_b32_e32 v159, v225, v159, vcc
	v_cmp_lt_i32_e32 vcc, v160, v163
	v_xor_b32_e32 v164, 1, v225
	s_waitcnt vmcnt(21)
	v_pk_add_f32 v[96:97], v[96:97], 1.0 op_sel_hi:[1,0]
	v_cndmask_b32_e32 v160, v225, v160, vcc
	v_cmp_lt_i32_e32 vcc, v161, v163
	v_pk_add_f32 v[94:95], v[94:95], 1.0 op_sel_hi:[1,0]
	s_waitcnt vmcnt(5)
	v_pk_add_f32 v[112:113], v[112:113], 1.0 op_sel_hi:[1,0]
	v_cndmask_b32_e32 v161, v225, v161, vcc
	v_cmp_lt_i32_e32 vcc, v162, v163
	v_pk_add_f32 v[110:111], v[110:111], 1.0 op_sel_hi:[1,0]
	v_pk_add_f32 v[92:93], v[92:93], 1.0 op_sel_hi:[1,0]
	v_cndmask_b32_e32 v162, v225, v162, vcc
	v_cmp_lt_i32_e32 vcc, v164, v163
	v_pk_add_f32 v[90:91], v[90:91], 1.0 op_sel_hi:[1,0]
	v_pk_add_f32 v[108:109], v[108:109], 1.0 op_sel_hi:[1,0]
	v_cndmask_b32_e32 v163, v225, v164, vcc
	v_pk_add_f32 v[106:107], v[106:107], 1.0 op_sel_hi:[1,0]
	v_pk_add_f32 v[88:89], v[88:89], 1.0 op_sel_hi:[1,0]
	v_pk_add_f32 v[86:87], v[86:87], 1.0 op_sel_hi:[1,0]
	v_pk_add_f32 v[104:105], v[104:105], 1.0 op_sel_hi:[1,0]
	v_pk_add_f32 v[102:103], v[102:103], 1.0 op_sel_hi:[1,0]
	v_pk_add_f32 v[84:85], v[84:85], 1.0 op_sel_hi:[1,0]
	v_pk_add_f32 v[82:83], v[82:83], 1.0 op_sel_hi:[1,0]
	s_waitcnt vmcnt(0)
	v_pk_add_f32 v[100:101], v[100:101], 1.0 op_sel_hi:[1,0]
	v_pk_add_f32 v[98:99], v[98:99], 1.0 op_sel_hi:[1,0]
	s_mov_b32 s6, 0
	v_lshlrev_b32_e32 v135, 2, v135
	v_lshlrev_b32_e32 v159, 2, v159
	v_lshlrev_b32_e32 v160, 2, v160
	v_lshlrev_b32_e32 v161, 2, v161
	v_lshlrev_b32_e32 v162, 2, v162
	v_lshlrev_b32_e32 v163, 2, v163
	s_add_i32 s26, s11, s6
	s_cmp_eq_u32 s6, 7
	s_cbranch_scc1 .LBB0_2147
	s_branch .LBB0_2142

; __device__ __forceinline__ void phase_row1(const Frame& F, int l) {
;     ...
;             if (i + 1 < 8) { if (l == 0) load_row(F.in[0] + (size_t)(row + 1) * D, lane, nx); else load_row_bf16(XB + (size_t)(row + 1) * D, lane, nx);
; #pragma unroll
;                 for (int j = 0; j < 4; ++j) ny[j] = *(const u32x2*)((const bf16*)(F.ws + WS_MIX) + (size_t)(row + 1) * D + 256 * j + 4 * lane); }
.LBB0_2142:
	s_add_i32 s44, s26, 1
	s_ashr_i32 s45, s44, 31
	s_and_b64 vcc, exec, s[28:29]
	s_cbranch_vccz .LBB0_2146
	s_lshl_b64 s[46:47], s[44:45], 11
	v_lshl_add_u64 v[14:15], v[116:117], 0, s[46:47]
	global_load_dwordx2 v[4:5], v[14:15], off nt
	global_load_dwordx2 v[8:9], v[14:15], off offset:512 nt
	global_load_dwordx2 v[12:13], v[14:15], off offset:1024 nt
	global_load_dwordx2 v[16:17], v[14:15], off offset:1536 nt
	s_cbranch_execnz .LBB0_2145
.LBB0_2144:
	s_lshl_b64 s[4:5], s[44:45], 12
	v_lshl_add_u64 v[14:15], v[128:129], 0, s[4:5]
	global_load_dwordx4 v[2:5], v[14:15], off nt
	global_load_dwordx4 v[6:9], v[14:15], off offset:1024 nt
	global_load_dwordx4 v[10:13], v[14:15], off offset:2048 nt
	s_nop 0
	global_load_dwordx4 v[14:17], v[14:15], off offset:3072 nt
	s_lshl_b64 s[46:47], s[44:45], 11
.LBB0_2145:
	v_lshl_add_u64 v[144:145], v[118:119], 0, s[46:47]
	global_load_dwordx2 v[138:139], v[144:145], off nt
	global_load_dwordx2 v[140:141], v[144:145], off offset:512 nt
	global_load_dwordx2 v[142:143], v[144:145], off offset:1024 nt
	s_nop 0
	global_load_dwordx2 v[144:145], v[144:145], off offset:1536 nt
	s_branch .LBB0_2147

; __device__ __forceinline__ void phase_row1(const Frame& F, int l) {
;     ...
;             const int fr = lane & 15, fq = lane >> 4, tile = w >> 1, nt = w & 1;
;             const float* wp = (const float*)(F.ws + WS_RWT) + ((size_t)l * NE + 16 * nt + fr) * D + 256 * fq;
;             const float* hp = H32 + (size_t)(chunk * 64 + 16 * tile + fr) * D + 256 * fq;
;             f32x4 c = {0.f, 0.f, 0.f, 0.f};
; #pragma unroll 16
;             for (int s4 = 0; s4 < 256; s4 += 4) { const f32x4 a = *(const f32x4*)(wp + s4), bq = *(const f32x4*)(hp + s4);
;                 c = __builtin_amdgcn_mfma_f32_16x16x4f32(a.x, bq.x, c, 0, 0, 0); c = __builtin_amdgcn_mfma_f32_16x16x4f32(a.y, bq.y, c, 0, 0, 0);
;                 c = __builtin_amdgcn_mfma_f32_16x16x4f32(a.z, bq.z, c, 0, 0, 0); c = __builtin_amdgcn_mfma_f32_16x16x4f32(a.w, bq.w, c, 0, 0, 0); }
.LBB0_2151:
	v_readfirstlane_b32 s4, v0
	v_readfirstlane_b32 s5, v134
	v_and_b32_e32 v22, 63, v0
	v_lshrrev_b32_e32 v23, 5, v22
	s_lshr_b32 s6, s4, 7
	s_lshl_b32 s6, s6, 4
	s_sub_i32 s5, s5, s6
	s_lshr_b32 s6, s4, 3
	s_add_i32 s5, s5, s6
	v_add_u32_e32 v24, s5, v23
	v_mov_b32_e32 v25, 0
	v_lshlrev_b64 v[24:25], 12, v[24:25]
	v_lshl_add_u64 v[24:25], s[78:79], 0, v[24:25]
	v_lshlrev_b32_e32 v26, 7, v22
	v_and_b32_e32 v26, 0xc00, v26
	v_and_b32_e32 v27, 7, v22
	v_xor_b32_e32 v27, v27, v23
	v_lshlrev_b32_e32 v27, 4, v27
	v_mov_b32_e32 v29, 0
	s_mov_b32 s7, 0
	s_mov_b32 s6, 0x11000000
	v_xor_b32_e32 v28, 0, v27
	v_or_b32_e32 v28, v28, v26
	v_lshl_add_u64 v[30:31], v[24:25], 0, s[6:7]
	v_lshl_add_u64 v[30:31], v[30:31], 0, v[28:29]
	s_mov_b32 s6, 0x11002000
	v_xor_b32_e32 v28, 32, v27
	v_or_b32_e32 v28, v28, v26
	v_lshl_add_u64 v[32:33], v[24:25], 0, s[6:7]
	v_lshl_add_u64 v[32:33], v[32:33], 0, v[28:29]
	s_mov_b32 s6, 0x11004000
	v_xor_b32_e32 v28, 64, v27
	v_or_b32_e32 v28, v28, v26
	v_lshl_add_u64 v[34:35], v[24:25], 0, s[6:7]
	v_lshl_add_u64 v[34:35], v[34:35], 0, v[28:29]
	s_mov_b32 s6, 0x11006000
	v_xor_b32_e32 v28, 0x60, v27
	v_or_b32_e32 v28, v28, v26
	v_lshl_add_u64 v[36:37], v[24:25], 0, s[6:7]
	v_lshl_add_u64 v[36:37], v[36:37], 0, v[28:29]
	s_lshl_b32 s5, s96, 5
	s_lshr_b32 s6, s4, 4
	s_add_i32 s5, s5, s6
	v_add_u32_e32 v24, s5, v23
	v_mov_b32_e32 v25, 0
	v_lshlrev_b64 v[24:25], 12, v[24:25]
	v_lshl_add_u64 v[24:25], s[78:79], 0, v[24:25]
	s_and_b32 s5, s4, 64
	s_add_i32 vcc_lo, s5, 0
	v_xor_b32_e32 v28, vcc_lo, v27
	v_or_b32_e32 v28, v28, v26
	s_mov_b32 s6, 0x70400000
	v_lshl_add_u64 v[38:39], v[24:25], 0, s[6:7]
	v_lshl_add_u64 v[38:39], v[38:39], 0, v[28:29]
	s_add_i32 vcc_lo, s5, 32
	v_xor_b32_e32 v28, vcc_lo, v27
	v_or_b32_e32 v28, v28, v26
	s_mov_b32 s6, 0x70402000
	v_lshl_add_u64 v[40:41], v[24:25], 0, s[6:7]
	v_lshl_add_u64 v[40:41], v[40:41], 0, v[28:29]
	v_and_b32_e32 v42, 15, v0
	v_lshlrev_b32_e32 v43, 9, v42
	v_and_b32_e32 v44, 7, v42
	v_lshl_or_b32 v43, v44, 4, v43
	v_lshrrev_b32_e32 v44, 4, v22
	v_lshl_or_b32 v43, v44, 7, v43
	s_lshr_b32 s5, s4, 7
	s_lshl_b32 s5, s5, 13
	s_add_i32 s5, s5, 0x8000
	v_add_u32_e32 v42, s5, v43
	s_and_b32 s5, s4, 64
	s_lshl_b32 s5, s5, 7
	s_add_i32 s5, s5, 0x10000
	v_add_u32_e32 v43, s5, v43
	s_lshl_b32 s5, s4, 6
	s_lshl_b32 s6, s4, 5
	s_mov_b64 vcc, 0x80
	s_add_i32 m0, s5, 0x8000
	s_nop 0
	global_load_lds_dwordx4 v[30:31], off nt
	s_add_i32 m0, s5, 0x8400
	s_nop 0
	global_load_lds_dwordx4 v[32:33], off nt
	s_add_i32 m0, s5, 0x8800
	s_nop 0
	global_load_lds_dwordx4 v[34:35], off nt
	s_add_i32 m0, s5, 0x8c00
	s_nop 0
	global_load_lds_dwordx4 v[36:37], off nt
	s_add_i32 m0, s6, 0x10000
	s_nop 0
	global_load_lds_dwordx4 v[38:39], off
	s_add_i32 m0, s6, 0x10400
	s_nop 0
	global_load_lds_dwordx4 v[40:41], off
	v_lshl_add_u64 v[30:31], v[30:31], 0, vcc
	v_lshl_add_u64 v[32:33], v[32:33], 0, vcc
	v_lshl_add_u64 v[34:35], v[34:35], 0, vcc
	v_lshl_add_u64 v[36:37], v[36:37], 0, vcc
	v_lshl_add_u64 v[38:39], v[38:39], 0, vcc
	v_lshl_add_u64 v[40:41], v[40:41], 0, vcc
	s_add_i32 m0, s5, 0x14000
	s_nop 0
	global_load_lds_dwordx4 v[30:31], off nt
	s_add_i32 m0, s5, 0x14400
	s_nop 0
	global_load_lds_dwordx4 v[32:33], off nt
	s_add_i32 m0, s5, 0x14800
	s_nop 0
	global_load_lds_dwordx4 v[34:35], off nt
	s_add_i32 m0, s5, 0x14c00
	s_nop 0
	global_load_lds_dwordx4 v[36:37], off nt
	s_add_i32 m0, s6, 0x1c000
	s_nop 0
	global_load_lds_dwordx4 v[38:39], off
	s_add_i32 m0, s6, 0x1c400
	s_nop 0
	global_load_lds_dwordx4 v[40:41], off
	v_lshl_add_u64 v[30:31], v[30:31], 0, vcc
	v_lshl_add_u64 v[32:33], v[32:33], 0, vcc
	v_lshl_add_u64 v[34:35], v[34:35], 0, vcc
	v_lshl_add_u64 v[36:37], v[36:37], 0, vcc
	v_lshl_add_u64 v[38:39], v[38:39], 0, vcc
	v_lshl_add_u64 v[40:41], v[40:41], 0, vcc
	s_waitcnt vmcnt(6)
	s_barrier
	ds_read_b128 v[46:49], v42
	ds_read_b128 v[78:81], v43
	v_xor_b32_e32 v44, 16, v42
	v_xor_b32_e32 v45, 16, v43
	ds_read_b128 v[50:53], v44
	ds_read_b128 v[82:85], v45
	v_xor_b32_e32 v44, 32, v42
	v_xor_b32_e32 v45, 32, v43
	ds_read_b128 v[54:57], v44
	ds_read_b128 v[86:89], v45
	v_xor_b32_e32 v44, 48, v42
	v_xor_b32_e32 v45, 48, v43
	ds_read_b128 v[58:61], v44
	ds_read_b128 v[90:93], v45
	v_xor_b32_e32 v44, 64, v42
	v_xor_b32_e32 v45, 64, v43
	ds_read_b128 v[62:65], v44
	ds_read_b128 v[94:97], v45
	v_xor_b32_e32 v44, 0x50, v42
	v_xor_b32_e32 v45, 0x50, v43
	ds_read_b128 v[66:69], v44
	ds_read_b128 v[98:101], v45
	v_xor_b32_e32 v44, 0x60, v42
	v_xor_b32_e32 v45, 0x60, v43
	ds_read_b128 v[70:73], v44
	ds_read_b128 v[102:105], v45
	v_xor_b32_e32 v44, 0x70, v42
	v_xor_b32_e32 v45, 0x70, v43
	ds_read_b128 v[74:77], v44
	ds_read_b128 v[106:109], v45
	s_waitcnt lgkmcnt(0)
	s_barrier
; __device__ __forceinline__ void phase_row1(const Frame& F, int l) {
;     ...
;             for (int s4 = 0; s4 < 256; s4 += 4) { const f32x4 a = *(const f32x4*)(wp + s4), bq = *(const f32x4*)(hp + s4);
;                 c = __builtin_amdgcn_mfma_f32_16x16x4f32(a.x, bq.x, c, 0, 0, 0); c = __builtin_amdgcn_mfma_f32_16x16x4f32(a.y, bq.y, c, 0, 0, 0);
;                 c = __builtin_amdgcn_mfma_f32_16x16x4f32(a.z, bq.z, c, 0, 0, 0); c = __builtin_amdgcn_mfma_f32_16x16x4f32(a.w, bq.w, c, 0, 0, 0); }
	s_add_i32 m0, s5, 0x8000
	s_nop 0
	global_load_lds_dwordx4 v[30:31], off nt
	s_add_i32 m0, s5, 0x8400
	s_nop 0
	global_load_lds_dwordx4 v[32:33], off nt
	s_add_i32 m0, s5, 0x8800
	s_nop 0
	global_load_lds_dwordx4 v[34:35], off nt
	s_add_i32 m0, s5, 0x8c00
	s_nop 0
	global_load_lds_dwordx4 v[36:37], off nt
	s_add_i32 m0, s6, 0x10000
	s_nop 0
	global_load_lds_dwordx4 v[38:39], off
	s_add_i32 m0, s6, 0x10400
	s_nop 0
	global_load_lds_dwordx4 v[40:41], off
	v_lshl_add_u64 v[30:31], v[30:31], 0, vcc
	v_lshl_add_u64 v[32:33], v[32:33], 0, vcc
	v_lshl_add_u64 v[34:35], v[34:35], 0, vcc
	v_lshl_add_u64 v[36:37], v[36:37], 0, vcc
	v_lshl_add_u64 v[38:39], v[38:39], 0, vcc
	v_lshl_add_u64 v[40:41], v[40:41], 0, vcc
	v_mfma_f32_16x16x4_f32 v[18:21], v78, v46, v[18:21]
	v_mfma_f32_16x16x4_f32 v[18:21], v79, v47, v[18:21]
	v_mfma_f32_16x16x4_f32 v[18:21], v80, v48, v[18:21]
	v_mfma_f32_16x16x4_f32 v[18:21], v81, v49, v[18:21]
	v_mfma_f32_16x16x4_f32 v[18:21], v82, v50, v[18:21]
	v_mfma_f32_16x16x4_f32 v[18:21], v83, v51, v[18:21]
	v_mfma_f32_16x16x4_f32 v[18:21], v84, v52, v[18:21]
	v_mfma_f32_16x16x4_f32 v[18:21], v85, v53, v[18:21]
	v_mfma_f32_16x16x4_f32 v[18:21], v86, v54, v[18:21]
	v_mfma_f32_16x16x4_f32 v[18:21], v87, v55, v[18:21]
	v_mfma_f32_16x16x4_f32 v[18:21], v88, v56, v[18:21]
	v_mfma_f32_16x16x4_f32 v[18:21], v89, v57, v[18:21]
	v_mfma_f32_16x16x4_f32 v[18:21], v90, v58, v[18:21]
	v_mfma_f32_16x16x4_f32 v[18:21], v91, v59, v[18:21]
	v_mfma_f32_16x16x4_f32 v[18:21], v92, v60, v[18:21]
	v_mfma_f32_16x16x4_f32 v[18:21], v93, v61, v[18:21]
	v_mfma_f32_16x16x4_f32 v[18:21], v94, v62, v[18:21]
	v_mfma_f32_16x16x4_f32 v[18:21], v95, v63, v[18:21]
	v_mfma_f32_16x16x4_f32 v[18:21], v96, v64, v[18:21]
	v_mfma_f32_16x16x4_f32 v[18:21], v97, v65, v[18:21]
	v_mfma_f32_16x16x4_f32 v[18:21], v98, v66, v[18:21]
	v_mfma_f32_16x16x4_f32 v[18:21], v99, v67, v[18:21]
	v_mfma_f32_16x16x4_f32 v[18:21], v100, v68, v[18:21]
	v_mfma_f32_16x16x4_f32 v[18:21], v101, v69, v[18:21]
	v_mfma_f32_16x16x4_f32 v[18:21], v102, v70, v[18:21]
	v_mfma_f32_16x16x4_f32 v[18:21], v103, v71, v[18:21]
	v_mfma_f32_16x16x4_f32 v[18:21], v104, v72, v[18:21]
	v_mfma_f32_16x16x4_f32 v[18:21], v105, v73, v[18:21]
	v_mfma_f32_16x16x4_f32 v[18:21], v106, v74, v[18:21]
	v_mfma_f32_16x16x4_f32 v[18:21], v107, v75, v[18:21]
	v_mfma_f32_16x16x4_f32 v[18:21], v108, v76, v[18:21]
	v_mfma_f32_16x16x4_f32 v[18:21], v109, v77, v[18:21]
	s_waitcnt vmcnt(6)
	s_barrier
	ds_read_b128 v[46:49], v42 offset:49152
	ds_read_b128 v[78:81], v43 offset:49152
	v_xor_b32_e32 v44, 16, v42
	v_xor_b32_e32 v45, 16, v43
	ds_read_b128 v[50:53], v44 offset:49152
	ds_read_b128 v[82:85], v45 offset:49152
	v_xor_b32_e32 v44, 32, v42
	v_xor_b32_e32 v45, 32, v43
	ds_read_b128 v[54:57], v44 offset:49152
	ds_read_b128 v[86:89], v45 offset:49152
	v_xor_b32_e32 v44, 48, v42
	v_xor_b32_e32 v45, 48, v43
	ds_read_b128 v[58:61], v44 offset:49152
	ds_read_b128 v[90:93], v45 offset:49152
	v_xor_b32_e32 v44, 64, v42
	v_xor_b32_e32 v45, 64, v43
	ds_read_b128 v[62:65], v44 offset:49152
	ds_read_b128 v[94:97], v45 offset:49152
	v_xor_b32_e32 v44, 0x50, v42
	v_xor_b32_e32 v45, 0x50, v43
	ds_read_b128 v[66:69], v44 offset:49152
	ds_read_b128 v[98:101], v45 offset:49152
	v_xor_b32_e32 v44, 0x60, v42
	v_xor_b32_e32 v45, 0x60, v43
	ds_read_b128 v[70:73], v44 offset:49152
	ds_read_b128 v[102:105], v45 offset:49152
	v_xor_b32_e32 v44, 0x70, v42
	v_xor_b32_e32 v45, 0x70, v43
	ds_read_b128 v[74:77], v44 offset:49152
	ds_read_b128 v[106:109], v45 offset:49152
	s_waitcnt lgkmcnt(0)
	s_barrier
	s_add_i32 m0, s5, 0x14000
	s_nop 0
	global_load_lds_dwordx4 v[30:31], off nt
	s_add_i32 m0, s5, 0x14400
	s_nop 0
	global_load_lds_dwordx4 v[32:33], off nt
	s_add_i32 m0, s5, 0x14800
	s_nop 0
	global_load_lds_dwordx4 v[34:35], off nt
	s_add_i32 m0, s5, 0x14c00
	s_nop 0
	global_load_lds_dwordx4 v[36:37], off nt
	s_add_i32 m0, s6, 0x1c000
	s_nop 0
	global_load_lds_dwordx4 v[38:39], off
	s_add_i32 m0, s6, 0x1c400
	s_nop 0
	global_load_lds_dwordx4 v[40:41], off
	v_lshl_add_u64 v[30:31], v[30:31], 0, vcc
	v_lshl_add_u64 v[32:33], v[32:33], 0, vcc
	v_lshl_add_u64 v[34:35], v[34:35], 0, vcc
	v_lshl_add_u64 v[36:37], v[36:37], 0, vcc
	v_lshl_add_u64 v[38:39], v[38:39], 0, vcc
	v_lshl_add_u64 v[40:41], v[40:41], 0, vcc
	v_mfma_f32_16x16x4_f32 v[18:21], v78, v46, v[18:21]
	v_mfma_f32_16x16x4_f32 v[18:21], v79, v47, v[18:21]
	v_mfma_f32_16x16x4_f32 v[18:21], v80, v48, v[18:21]
	v_mfma_f32_16x16x4_f32 v[18:21], v81, v49, v[18:21]
	v_mfma_f32_16x16x4_f32 v[18:21], v82, v50, v[18:21]
	v_mfma_f32_16x16x4_f32 v[18:21], v83, v51, v[18:21]
	v_mfma_f32_16x16x4_f32 v[18:21], v84, v52, v[18:21]
	v_mfma_f32_16x16x4_f32 v[18:21], v85, v53, v[18:21]
	v_mfma_f32_16x16x4_f32 v[18:21], v86, v54, v[18:21]
	v_mfma_f32_16x16x4_f32 v[18:21], v87, v55, v[18:21]
	v_mfma_f32_16x16x4_f32 v[18:21], v88, v56, v[18:21]
	v_mfma_f32_16x16x4_f32 v[18:21], v89, v57, v[18:21]
	v_mfma_f32_16x16x4_f32 v[18:21], v90, v58, v[18:21]
	v_mfma_f32_16x16x4_f32 v[18:21], v91, v59, v[18:21]
	v_mfma_f32_16x16x4_f32 v[18:21], v92, v60, v[18:21]
	v_mfma_f32_16x16x4_f32 v[18:21], v93, v61, v[18:21]
	v_mfma_f32_16x16x4_f32 v[18:21], v94, v62, v[18:21]
	v_mfma_f32_16x16x4_f32 v[18:21], v95, v63, v[18:21]
	v_mfma_f32_16x16x4_f32 v[18:21], v96, v64, v[18:21]
	v_mfma_f32_16x16x4_f32 v[18:21], v97, v65, v[18:21]
	v_mfma_f32_16x16x4_f32 v[18:21], v98, v66, v[18:21]
	v_mfma_f32_16x16x4_f32 v[18:21], v99, v67, v[18:21]
	v_mfma_f32_16x16x4_f32 v[18:21], v100, v68, v[18:21]
	v_mfma_f32_16x16x4_f32 v[18:21], v101, v69, v[18:21]
	v_mfma_f32_16x16x4_f32 v[18:21], v102, v70, v[18:21]
	v_mfma_f32_16x16x4_f32 v[18:21], v103, v71, v[18:21]
	v_mfma_f32_16x16x4_f32 v[18:21], v104, v72, v[18:21]
	v_mfma_f32_16x16x4_f32 v[18:21], v105, v73, v[18:21]
	v_mfma_f32_16x16x4_f32 v[18:21], v106, v74, v[18:21]
	v_mfma_f32_16x16x4_f32 v[18:21], v107, v75, v[18:21]
	v_mfma_f32_16x16x4_f32 v[18:21], v108, v76, v[18:21]
	v_mfma_f32_16x16x4_f32 v[18:21], v109, v77, v[18:21]
	s_waitcnt vmcnt(6)
	s_barrier
; __device__ __forceinline__ void phase_row1(const Frame& F, int l) {
;     ...
;             for (int s4 = 0; s4 < 256; s4 += 4) { const f32x4 a = *(const f32x4*)(wp + s4), bq = *(const f32x4*)(hp + s4);
;                 c = __builtin_amdgcn_mfma_f32_16x16x4f32(a.x, bq.x, c, 0, 0, 0); c = __builtin_amdgcn_mfma_f32_16x16x4f32(a.y, bq.y, c, 0, 0, 0);
;                 c = __builtin_amdgcn_mfma_f32_16x16x4f32(a.z, bq.z, c, 0, 0, 0); c = __builtin_amdgcn_mfma_f32_16x16x4f32(a.w, bq.w, c, 0, 0, 0); }
	ds_read_b128 v[46:49], v42
	ds_read_b128 v[78:81], v43
	v_xor_b32_e32 v44, 16, v42
	v_xor_b32_e32 v45, 16, v43
	ds_read_b128 v[50:53], v44
	ds_read_b128 v[82:85], v45
	v_xor_b32_e32 v44, 32, v42
	v_xor_b32_e32 v45, 32, v43
	ds_read_b128 v[54:57], v44
	ds_read_b128 v[86:89], v45
	v_xor_b32_e32 v44, 48, v42
	v_xor_b32_e32 v45, 48, v43
	ds_read_b128 v[58:61], v44
	ds_read_b128 v[90:93], v45
	v_xor_b32_e32 v44, 64, v42
	v_xor_b32_e32 v45, 64, v43
	ds_read_b128 v[62:65], v44
	ds_read_b128 v[94:97], v45
	v_xor_b32_e32 v44, 0x50, v42
	v_xor_b32_e32 v45, 0x50, v43
	ds_read_b128 v[66:69], v44
	ds_read_b128 v[98:101], v45
	v_xor_b32_e32 v44, 0x60, v42
	v_xor_b32_e32 v45, 0x60, v43
	ds_read_b128 v[70:73], v44
	ds_read_b128 v[102:105], v45
	v_xor_b32_e32 v44, 0x70, v42
	v_xor_b32_e32 v45, 0x70, v43
	ds_read_b128 v[74:77], v44
	ds_read_b128 v[106:109], v45
	s_waitcnt lgkmcnt(0)
	s_barrier
	s_add_i32 m0, s5, 0x8000
	s_nop 0
	global_load_lds_dwordx4 v[30:31], off nt
	s_add_i32 m0, s5, 0x8400
	s_nop 0
	global_load_lds_dwordx4 v[32:33], off nt
	s_add_i32 m0, s5, 0x8800
	s_nop 0
	global_load_lds_dwordx4 v[34:35], off nt
	s_add_i32 m0, s5, 0x8c00
	s_nop 0
	global_load_lds_dwordx4 v[36:37], off nt
	s_add_i32 m0, s6, 0x10000
	s_nop 0
	global_load_lds_dwordx4 v[38:39], off
	s_add_i32 m0, s6, 0x10400
	s_nop 0
	global_load_lds_dwordx4 v[40:41], off
	v_lshl_add_u64 v[30:31], v[30:31], 0, vcc
	v_lshl_add_u64 v[32:33], v[32:33], 0, vcc
	v_lshl_add_u64 v[34:35], v[34:35], 0, vcc
	v_lshl_add_u64 v[36:37], v[36:37], 0, vcc
	v_lshl_add_u64 v[38:39], v[38:39], 0, vcc
	v_lshl_add_u64 v[40:41], v[40:41], 0, vcc
	v_mfma_f32_16x16x4_f32 v[18:21], v78, v46, v[18:21]
	v_mfma_f32_16x16x4_f32 v[18:21], v79, v47, v[18:21]
	v_mfma_f32_16x16x4_f32 v[18:21], v80, v48, v[18:21]
	v_mfma_f32_16x16x4_f32 v[18:21], v81, v49, v[18:21]
	v_mfma_f32_16x16x4_f32 v[18:21], v82, v50, v[18:21]
	v_mfma_f32_16x16x4_f32 v[18:21], v83, v51, v[18:21]
	v_mfma_f32_16x16x4_f32 v[18:21], v84, v52, v[18:21]
	v_mfma_f32_16x16x4_f32 v[18:21], v85, v53, v[18:21]
	v_mfma_f32_16x16x4_f32 v[18:21], v86, v54, v[18:21]
	v_mfma_f32_16x16x4_f32 v[18:21], v87, v55, v[18:21]
	v_mfma_f32_16x16x4_f32 v[18:21], v88, v56, v[18:21]
	v_mfma_f32_16x16x4_f32 v[18:21], v89, v57, v[18:21]
	v_mfma_f32_16x16x4_f32 v[18:21], v90, v58, v[18:21]
	v_mfma_f32_16x16x4_f32 v[18:21], v91, v59, v[18:21]
	v_mfma_f32_16x16x4_f32 v[18:21], v92, v60, v[18:21]
	v_mfma_f32_16x16x4_f32 v[18:21], v93, v61, v[18:21]
	v_mfma_f32_16x16x4_f32 v[18:21], v94, v62, v[18:21]
	v_mfma_f32_16x16x4_f32 v[18:21], v95, v63, v[18:21]
	v_mfma_f32_16x16x4_f32 v[18:21], v96, v64, v[18:21]
	v_mfma_f32_16x16x4_f32 v[18:21], v97, v65, v[18:21]
	v_mfma_f32_16x16x4_f32 v[18:21], v98, v66, v[18:21]
	v_mfma_f32_16x16x4_f32 v[18:21], v99, v67, v[18:21]
	v_mfma_f32_16x16x4_f32 v[18:21], v100, v68, v[18:21]
	v_mfma_f32_16x16x4_f32 v[18:21], v101, v69, v[18:21]
	v_mfma_f32_16x16x4_f32 v[18:21], v102, v70, v[18:21]
	v_mfma_f32_16x16x4_f32 v[18:21], v103, v71, v[18:21]
	v_mfma_f32_16x16x4_f32 v[18:21], v104, v72, v[18:21]
	v_mfma_f32_16x16x4_f32 v[18:21], v105, v73, v[18:21]
	v_mfma_f32_16x16x4_f32 v[18:21], v106, v74, v[18:21]
	v_mfma_f32_16x16x4_f32 v[18:21], v107, v75, v[18:21]
	v_mfma_f32_16x16x4_f32 v[18:21], v108, v76, v[18:21]
	v_mfma_f32_16x16x4_f32 v[18:21], v109, v77, v[18:21]
	s_waitcnt vmcnt(6)
	s_barrier
	ds_read_b128 v[46:49], v42 offset:49152
	ds_read_b128 v[78:81], v43 offset:49152
	v_xor_b32_e32 v44, 16, v42
	v_xor_b32_e32 v45, 16, v43
	ds_read_b128 v[50:53], v44 offset:49152
	ds_read_b128 v[82:85], v45 offset:49152
	v_xor_b32_e32 v44, 32, v42
	v_xor_b32_e32 v45, 32, v43
	ds_read_b128 v[54:57], v44 offset:49152
	ds_read_b128 v[86:89], v45 offset:49152
	v_xor_b32_e32 v44, 48, v42
	v_xor_b32_e32 v45, 48, v43
	ds_read_b128 v[58:61], v44 offset:49152
	ds_read_b128 v[90:93], v45 offset:49152
	v_xor_b32_e32 v44, 64, v42
	v_xor_b32_e32 v45, 64, v43
	ds_read_b128 v[62:65], v44 offset:49152
	ds_read_b128 v[94:97], v45 offset:49152
	v_xor_b32_e32 v44, 0x50, v42
	v_xor_b32_e32 v45, 0x50, v43
	ds_read_b128 v[66:69], v44 offset:49152
	ds_read_b128 v[98:101], v45 offset:49152
	v_xor_b32_e32 v44, 0x60, v42
	v_xor_b32_e32 v45, 0x60, v43
	ds_read_b128 v[70:73], v44 offset:49152
	ds_read_b128 v[102:105], v45 offset:49152
	v_xor_b32_e32 v44, 0x70, v42
	v_xor_b32_e32 v45, 0x70, v43
	ds_read_b128 v[74:77], v44 offset:49152
	ds_read_b128 v[106:109], v45 offset:49152
	s_waitcnt lgkmcnt(0)
	s_barrier
; __device__ __forceinline__ void phase_row1(const Frame& F, int l) {
;     ...
;             for (int s4 = 0; s4 < 256; s4 += 4) { const f32x4 a = *(const f32x4*)(wp + s4), bq = *(const f32x4*)(hp + s4);
;                 c = __builtin_amdgcn_mfma_f32_16x16x4f32(a.x, bq.x, c, 0, 0, 0); c = __builtin_amdgcn_mfma_f32_16x16x4f32(a.y, bq.y, c, 0, 0, 0);
;                 c = __builtin_amdgcn_mfma_f32_16x16x4f32(a.z, bq.z, c, 0, 0, 0); c = __builtin_amdgcn_mfma_f32_16x16x4f32(a.w, bq.w, c, 0, 0, 0); }
	s_add_i32 m0, s5, 0x14000
	s_nop 0
	global_load_lds_dwordx4 v[30:31], off nt
	s_add_i32 m0, s5, 0x14400
	s_nop 0
	global_load_lds_dwordx4 v[32:33], off nt
	s_add_i32 m0, s5, 0x14800
	s_nop 0
	global_load_lds_dwordx4 v[34:35], off nt
	s_add_i32 m0, s5, 0x14c00
	s_nop 0
	global_load_lds_dwordx4 v[36:37], off nt
	s_add_i32 m0, s6, 0x1c000
	s_nop 0
	global_load_lds_dwordx4 v[38:39], off
	s_add_i32 m0, s6, 0x1c400
	s_nop 0
	global_load_lds_dwordx4 v[40:41], off
	v_lshl_add_u64 v[30:31], v[30:31], 0, vcc
	v_lshl_add_u64 v[32:33], v[32:33], 0, vcc
	v_lshl_add_u64 v[34:35], v[34:35], 0, vcc
	v_lshl_add_u64 v[36:37], v[36:37], 0, vcc
	v_lshl_add_u64 v[38:39], v[38:39], 0, vcc
	v_lshl_add_u64 v[40:41], v[40:41], 0, vcc
	v_mfma_f32_16x16x4_f32 v[18:21], v78, v46, v[18:21]
	v_mfma_f32_16x16x4_f32 v[18:21], v79, v47, v[18:21]
	v_mfma_f32_16x16x4_f32 v[18:21], v80, v48, v[18:21]
	v_mfma_f32_16x16x4_f32 v[18:21], v81, v49, v[18:21]
	v_mfma_f32_16x16x4_f32 v[18:21], v82, v50, v[18:21]
	v_mfma_f32_16x16x4_f32 v[18:21], v83, v51, v[18:21]
	v_mfma_f32_16x16x4_f32 v[18:21], v84, v52, v[18:21]
	v_mfma_f32_16x16x4_f32 v[18:21], v85, v53, v[18:21]
	v_mfma_f32_16x16x4_f32 v[18:21], v86, v54, v[18:21]
	v_mfma_f32_16x16x4_f32 v[18:21], v87, v55, v[18:21]
	v_mfma_f32_16x16x4_f32 v[18:21], v88, v56, v[18:21]
	v_mfma_f32_16x16x4_f32 v[18:21], v89, v57, v[18:21]
	v_mfma_f32_16x16x4_f32 v[18:21], v90, v58, v[18:21]
	v_mfma_f32_16x16x4_f32 v[18:21], v91, v59, v[18:21]
	v_mfma_f32_16x16x4_f32 v[18:21], v92, v60, v[18:21]
	v_mfma_f32_16x16x4_f32 v[18:21], v93, v61, v[18:21]
	v_mfma_f32_16x16x4_f32 v[18:21], v94, v62, v[18:21]
	v_mfma_f32_16x16x4_f32 v[18:21], v95, v63, v[18:21]
	v_mfma_f32_16x16x4_f32 v[18:21], v96, v64, v[18:21]
	v_mfma_f32_16x16x4_f32 v[18:21], v97, v65, v[18:21]
	v_mfma_f32_16x16x4_f32 v[18:21], v98, v66, v[18:21]
	v_mfma_f32_16x16x4_f32 v[18:21], v99, v67, v[18:21]
	v_mfma_f32_16x16x4_f32 v[18:21], v100, v68, v[18:21]
	v_mfma_f32_16x16x4_f32 v[18:21], v101, v69, v[18:21]
	v_mfma_f32_16x16x4_f32 v[18:21], v102, v70, v[18:21]
	v_mfma_f32_16x16x4_f32 v[18:21], v103, v71, v[18:21]
	v_mfma_f32_16x16x4_f32 v[18:21], v104, v72, v[18:21]
	v_mfma_f32_16x16x4_f32 v[18:21], v105, v73, v[18:21]
	v_mfma_f32_16x16x4_f32 v[18:21], v106, v74, v[18:21]
	v_mfma_f32_16x16x4_f32 v[18:21], v107, v75, v[18:21]
	v_mfma_f32_16x16x4_f32 v[18:21], v108, v76, v[18:21]
	v_mfma_f32_16x16x4_f32 v[18:21], v109, v77, v[18:21]
	s_waitcnt vmcnt(6)
	s_barrier
	ds_read_b128 v[46:49], v42
	ds_read_b128 v[78:81], v43
	v_xor_b32_e32 v44, 16, v42
	v_xor_b32_e32 v45, 16, v43
	ds_read_b128 v[50:53], v44
	ds_read_b128 v[82:85], v45
	v_xor_b32_e32 v44, 32, v42
	v_xor_b32_e32 v45, 32, v43
	ds_read_b128 v[54:57], v44
	ds_read_b128 v[86:89], v45
	v_xor_b32_e32 v44, 48, v42
	v_xor_b32_e32 v45, 48, v43
	ds_read_b128 v[58:61], v44
	ds_read_b128 v[90:93], v45
	v_xor_b32_e32 v44, 64, v42
	v_xor_b32_e32 v45, 64, v43
	ds_read_b128 v[62:65], v44
	ds_read_b128 v[94:97], v45
	v_xor_b32_e32 v44, 0x50, v42
	v_xor_b32_e32 v45, 0x50, v43
	ds_read_b128 v[66:69], v44
	ds_read_b128 v[98:101], v45
	v_xor_b32_e32 v44, 0x60, v42
	v_xor_b32_e32 v45, 0x60, v43
	ds_read_b128 v[70:73], v44
	ds_read_b128 v[102:105], v45
	v_xor_b32_e32 v44, 0x70, v42
	v_xor_b32_e32 v45, 0x70, v43
	ds_read_b128 v[74:77], v44
	ds_read_b128 v[106:109], v45
	s_waitcnt lgkmcnt(0)
	s_barrier
	s_add_i32 m0, s5, 0x8000
	s_nop 0
	global_load_lds_dwordx4 v[30:31], off nt
	s_add_i32 m0, s5, 0x8400
	s_nop 0
	global_load_lds_dwordx4 v[32:33], off nt
	s_add_i32 m0, s5, 0x8800
	s_nop 0
	global_load_lds_dwordx4 v[34:35], off nt
	s_add_i32 m0, s5, 0x8c00
	s_nop 0
	global_load_lds_dwordx4 v[36:37], off nt
	s_add_i32 m0, s6, 0x10000
	s_nop 0
	global_load_lds_dwordx4 v[38:39], off
	s_add_i32 m0, s6, 0x10400
	s_nop 0
	global_load_lds_dwordx4 v[40:41], off
	v_lshl_add_u64 v[30:31], v[30:31], 0, vcc
	v_lshl_add_u64 v[32:33], v[32:33], 0, vcc
	v_lshl_add_u64 v[34:35], v[34:35], 0, vcc
	v_lshl_add_u64 v[36:37], v[36:37], 0, vcc
	v_lshl_add_u64 v[38:39], v[38:39], 0, vcc
	v_lshl_add_u64 v[40:41], v[40:41], 0, vcc
	v_mfma_f32_16x16x4_f32 v[18:21], v78, v46, v[18:21]
	v_mfma_f32_16x16x4_f32 v[18:21], v79, v47, v[18:21]
	v_mfma_f32_16x16x4_f32 v[18:21], v80, v48, v[18:21]
	v_mfma_f32_16x16x4_f32 v[18:21], v81, v49, v[18:21]
	v_mfma_f32_16x16x4_f32 v[18:21], v82, v50, v[18:21]
	v_mfma_f32_16x16x4_f32 v[18:21], v83, v51, v[18:21]
	v_mfma_f32_16x16x4_f32 v[18:21], v84, v52, v[18:21]
	v_mfma_f32_16x16x4_f32 v[18:21], v85, v53, v[18:21]
	v_mfma_f32_16x16x4_f32 v[18:21], v86, v54, v[18:21]
	v_mfma_f32_16x16x4_f32 v[18:21], v87, v55, v[18:21]
	v_mfma_f32_16x16x4_f32 v[18:21], v88, v56, v[18:21]
	v_mfma_f32_16x16x4_f32 v[18:21], v89, v57, v[18:21]
	v_mfma_f32_16x16x4_f32 v[18:21], v90, v58, v[18:21]
	v_mfma_f32_16x16x4_f32 v[18:21], v91, v59, v[18:21]
	v_mfma_f32_16x16x4_f32 v[18:21], v92, v60, v[18:21]
	v_mfma_f32_16x16x4_f32 v[18:21], v93, v61, v[18:21]
	v_mfma_f32_16x16x4_f32 v[18:21], v94, v62, v[18:21]
	v_mfma_f32_16x16x4_f32 v[18:21], v95, v63, v[18:21]
	v_mfma_f32_16x16x4_f32 v[18:21], v96, v64, v[18:21]
	v_mfma_f32_16x16x4_f32 v[18:21], v97, v65, v[18:21]
	v_mfma_f32_16x16x4_f32 v[18:21], v98, v66, v[18:21]
	v_mfma_f32_16x16x4_f32 v[18:21], v99, v67, v[18:21]
	v_mfma_f32_16x16x4_f32 v[18:21], v100, v68, v[18:21]
	v_mfma_f32_16x16x4_f32 v[18:21], v101, v69, v[18:21]
	v_mfma_f32_16x16x4_f32 v[18:21], v102, v70, v[18:21]
	v_mfma_f32_16x16x4_f32 v[18:21], v103, v71, v[18:21]
	v_mfma_f32_16x16x4_f32 v[18:21], v104, v72, v[18:21]
	v_mfma_f32_16x16x4_f32 v[18:21], v105, v73, v[18:21]
	v_mfma_f32_16x16x4_f32 v[18:21], v106, v74, v[18:21]
	v_mfma_f32_16x16x4_f32 v[18:21], v107, v75, v[18:21]
	v_mfma_f32_16x16x4_f32 v[18:21], v108, v76, v[18:21]
	v_mfma_f32_16x16x4_f32 v[18:21], v109, v77, v[18:21]
	s_waitcnt vmcnt(6)
	s_barrier
; __device__ __forceinline__ void phase_row1(const Frame& F, int l) {
;     ...
;             for (int s4 = 0; s4 < 256; s4 += 4) { const f32x4 a = *(const f32x4*)(wp + s4), bq = *(const f32x4*)(hp + s4);
;                 c = __builtin_amdgcn_mfma_f32_16x16x4f32(a.x, bq.x, c, 0, 0, 0); c = __builtin_amdgcn_mfma_f32_16x16x4f32(a.y, bq.y, c, 0, 0, 0);
;                 c = __builtin_amdgcn_mfma_f32_16x16x4f32(a.z, bq.z, c, 0, 0, 0); c = __builtin_amdgcn_mfma_f32_16x16x4f32(a.w, bq.w, c, 0, 0, 0); }
	ds_read_b128 v[46:49], v42 offset:49152
	ds_read_b128 v[78:81], v43 offset:49152
	v_xor_b32_e32 v44, 16, v42
	v_xor_b32_e32 v45, 16, v43
	ds_read_b128 v[50:53], v44 offset:49152
	ds_read_b128 v[82:85], v45 offset:49152
	v_xor_b32_e32 v44, 32, v42
	v_xor_b32_e32 v45, 32, v43
	ds_read_b128 v[54:57], v44 offset:49152
	ds_read_b128 v[86:89], v45 offset:49152
	v_xor_b32_e32 v44, 48, v42
	v_xor_b32_e32 v45, 48, v43
	ds_read_b128 v[58:61], v44 offset:49152
	ds_read_b128 v[90:93], v45 offset:49152
	v_xor_b32_e32 v44, 64, v42
	v_xor_b32_e32 v45, 64, v43
	ds_read_b128 v[62:65], v44 offset:49152
	ds_read_b128 v[94:97], v45 offset:49152
	v_xor_b32_e32 v44, 0x50, v42
	v_xor_b32_e32 v45, 0x50, v43
	ds_read_b128 v[66:69], v44 offset:49152
	ds_read_b128 v[98:101], v45 offset:49152
	v_xor_b32_e32 v44, 0x60, v42
	v_xor_b32_e32 v45, 0x60, v43
	ds_read_b128 v[70:73], v44 offset:49152
	ds_read_b128 v[102:105], v45 offset:49152
	v_xor_b32_e32 v44, 0x70, v42
	v_xor_b32_e32 v45, 0x70, v43
	ds_read_b128 v[74:77], v44 offset:49152
	ds_read_b128 v[106:109], v45 offset:49152
	s_waitcnt lgkmcnt(0)
	s_barrier
	s_add_i32 m0, s5, 0x14000
	s_nop 0
	global_load_lds_dwordx4 v[30:31], off nt
	s_add_i32 m0, s5, 0x14400
	s_nop 0
	global_load_lds_dwordx4 v[32:33], off nt
	s_add_i32 m0, s5, 0x14800
	s_nop 0
	global_load_lds_dwordx4 v[34:35], off nt
	s_add_i32 m0, s5, 0x14c00
	s_nop 0
	global_load_lds_dwordx4 v[36:37], off nt
	s_add_i32 m0, s6, 0x1c000
	s_nop 0
	global_load_lds_dwordx4 v[38:39], off
	s_add_i32 m0, s6, 0x1c400
	s_nop 0
	global_load_lds_dwordx4 v[40:41], off
	v_lshl_add_u64 v[30:31], v[30:31], 0, vcc
	v_lshl_add_u64 v[32:33], v[32:33], 0, vcc
	v_lshl_add_u64 v[34:35], v[34:35], 0, vcc
	v_lshl_add_u64 v[36:37], v[36:37], 0, vcc
	v_lshl_add_u64 v[38:39], v[38:39], 0, vcc
	v_lshl_add_u64 v[40:41], v[40:41], 0, vcc
	v_mfma_f32_16x16x4_f32 v[18:21], v78, v46, v[18:21]
	v_mfma_f32_16x16x4_f32 v[18:21], v79, v47, v[18:21]
	v_mfma_f32_16x16x4_f32 v[18:21], v80, v48, v[18:21]
	v_mfma_f32_16x16x4_f32 v[18:21], v81, v49, v[18:21]
	v_mfma_f32_16x16x4_f32 v[18:21], v82, v50, v[18:21]
	v_mfma_f32_16x16x4_f32 v[18:21], v83, v51, v[18:21]
	v_mfma_f32_16x16x4_f32 v[18:21], v84, v52, v[18:21]
	v_mfma_f32_16x16x4_f32 v[18:21], v85, v53, v[18:21]
	v_mfma_f32_16x16x4_f32 v[18:21], v86, v54, v[18:21]
	v_mfma_f32_16x16x4_f32 v[18:21], v87, v55, v[18:21]
	v_mfma_f32_16x16x4_f32 v[18:21], v88, v56, v[18:21]
	v_mfma_f32_16x16x4_f32 v[18:21], v89, v57, v[18:21]
	v_mfma_f32_16x16x4_f32 v[18:21], v90, v58, v[18:21]
	v_mfma_f32_16x16x4_f32 v[18:21], v91, v59, v[18:21]
	v_mfma_f32_16x16x4_f32 v[18:21], v92, v60, v[18:21]
	v_mfma_f32_16x16x4_f32 v[18:21], v93, v61, v[18:21]
	v_mfma_f32_16x16x4_f32 v[18:21], v94, v62, v[18:21]
	v_mfma_f32_16x16x4_f32 v[18:21], v95, v63, v[18:21]
	v_mfma_f32_16x16x4_f32 v[18:21], v96, v64, v[18:21]
	v_mfma_f32_16x16x4_f32 v[18:21], v97, v65, v[18:21]
	v_mfma_f32_16x16x4_f32 v[18:21], v98, v66, v[18:21]
	v_mfma_f32_16x16x4_f32 v[18:21], v99, v67, v[18:21]
	v_mfma_f32_16x16x4_f32 v[18:21], v100, v68, v[18:21]
	v_mfma_f32_16x16x4_f32 v[18:21], v101, v69, v[18:21]
	v_mfma_f32_16x16x4_f32 v[18:21], v102, v70, v[18:21]
	v_mfma_f32_16x16x4_f32 v[18:21], v103, v71, v[18:21]
	v_mfma_f32_16x16x4_f32 v[18:21], v104, v72, v[18:21]
	v_mfma_f32_16x16x4_f32 v[18:21], v105, v73, v[18:21]
	v_mfma_f32_16x16x4_f32 v[18:21], v106, v74, v[18:21]
	v_mfma_f32_16x16x4_f32 v[18:21], v107, v75, v[18:21]
	v_mfma_f32_16x16x4_f32 v[18:21], v108, v76, v[18:21]
	v_mfma_f32_16x16x4_f32 v[18:21], v109, v77, v[18:21]
	s_waitcnt vmcnt(6)
	s_barrier
	ds_read_b128 v[46:49], v42
	ds_read_b128 v[78:81], v43
	v_xor_b32_e32 v44, 16, v42
	v_xor_b32_e32 v45, 16, v43
	ds_read_b128 v[50:53], v44
	ds_read_b128 v[82:85], v45
	v_xor_b32_e32 v44, 32, v42
	v_xor_b32_e32 v45, 32, v43
	ds_read_b128 v[54:57], v44
	ds_read_b128 v[86:89], v45
	v_xor_b32_e32 v44, 48, v42
	v_xor_b32_e32 v45, 48, v43
	ds_read_b128 v[58:61], v44
	ds_read_b128 v[90:93], v45
	v_xor_b32_e32 v44, 64, v42
	v_xor_b32_e32 v45, 64, v43
	ds_read_b128 v[62:65], v44
	ds_read_b128 v[94:97], v45
	v_xor_b32_e32 v44, 0x50, v42
	v_xor_b32_e32 v45, 0x50, v43
	ds_read_b128 v[66:69], v44
	ds_read_b128 v[98:101], v45
	v_xor_b32_e32 v44, 0x60, v42
	v_xor_b32_e32 v45, 0x60, v43
	ds_read_b128 v[70:73], v44
	ds_read_b128 v[102:105], v45
	v_xor_b32_e32 v44, 0x70, v42
	v_xor_b32_e32 v45, 0x70, v43
	ds_read_b128 v[74:77], v44
	ds_read_b128 v[106:109], v45
	s_waitcnt lgkmcnt(14)
	v_mfma_f32_16x16x4_f32 v[18:21], v78, v46, v[18:21]
	v_mfma_f32_16x16x4_f32 v[18:21], v79, v47, v[18:21]
	v_mfma_f32_16x16x4_f32 v[18:21], v80, v48, v[18:21]
	v_mfma_f32_16x16x4_f32 v[18:21], v81, v49, v[18:21]
	s_waitcnt lgkmcnt(12)
	v_mfma_f32_16x16x4_f32 v[18:21], v82, v50, v[18:21]
	v_mfma_f32_16x16x4_f32 v[18:21], v83, v51, v[18:21]
	v_mfma_f32_16x16x4_f32 v[18:21], v84, v52, v[18:21]
	v_mfma_f32_16x16x4_f32 v[18:21], v85, v53, v[18:21]
	s_waitcnt lgkmcnt(10)
	v_mfma_f32_16x16x4_f32 v[18:21], v86, v54, v[18:21]
	v_mfma_f32_16x16x4_f32 v[18:21], v87, v55, v[18:21]
	v_mfma_f32_16x16x4_f32 v[18:21], v88, v56, v[18:21]
	v_mfma_f32_16x16x4_f32 v[18:21], v89, v57, v[18:21]
	s_waitcnt lgkmcnt(8)
	v_mfma_f32_16x16x4_f32 v[18:21], v90, v58, v[18:21]
	v_mfma_f32_16x16x4_f32 v[18:21], v91, v59, v[18:21]
	v_mfma_f32_16x16x4_f32 v[18:21], v92, v60, v[18:21]
	v_mfma_f32_16x16x4_f32 v[18:21], v93, v61, v[18:21]
	s_waitcnt lgkmcnt(6)
	v_mfma_f32_16x16x4_f32 v[18:21], v94, v62, v[18:21]
	v_mfma_f32_16x16x4_f32 v[18:21], v95, v63, v[18:21]
	v_mfma_f32_16x16x4_f32 v[18:21], v96, v64, v[18:21]
	v_mfma_f32_16x16x4_f32 v[18:21], v97, v65, v[18:21]
	s_waitcnt lgkmcnt(4)
	v_mfma_f32_16x16x4_f32 v[18:21], v98, v66, v[18:21]
	v_mfma_f32_16x16x4_f32 v[18:21], v99, v67, v[18:21]
	v_mfma_f32_16x16x4_f32 v[18:21], v100, v68, v[18:21]
	v_mfma_f32_16x16x4_f32 v[18:21], v101, v69, v[18:21]
	s_waitcnt lgkmcnt(2)
	v_mfma_f32_16x16x4_f32 v[18:21], v102, v70, v[18:21]
	v_mfma_f32_16x16x4_f32 v[18:21], v103, v71, v[18:21]
	v_mfma_f32_16x16x4_f32 v[18:21], v104, v72, v[18:21]
	v_mfma_f32_16x16x4_f32 v[18:21], v105, v73, v[18:21]
	s_waitcnt lgkmcnt(0)
	v_mfma_f32_16x16x4_f32 v[18:21], v106, v74, v[18:21]
	v_mfma_f32_16x16x4_f32 v[18:21], v107, v75, v[18:21]
	v_mfma_f32_16x16x4_f32 v[18:21], v108, v76, v[18:21]
	v_mfma_f32_16x16x4_f32 v[18:21], v109, v77, v[18:21]
	s_waitcnt vmcnt(0)
	s_barrier
; __device__ __forceinline__ void phase_row1(const Frame& F, int l) {
;     ...
;             for (int s4 = 0; s4 < 256; s4 += 4) { const f32x4 a = *(const f32x4*)(wp + s4), bq = *(const f32x4*)(hp + s4);
;                 c = __builtin_amdgcn_mfma_f32_16x16x4f32(a.x, bq.x, c, 0, 0, 0); c = __builtin_amdgcn_mfma_f32_16x16x4f32(a.y, bq.y, c, 0, 0, 0);
;                 c = __builtin_amdgcn_mfma_f32_16x16x4f32(a.z, bq.z, c, 0, 0, 0); c = __builtin_amdgcn_mfma_f32_16x16x4f32(a.w, bq.w, c, 0, 0, 0); }
; #pragma unroll
;             for (int j = 0; j < 4; ++j) { const int e = 16 * nt + 4 * fq + j; lg[(16 * tile + fr) * 33 + e] = c[j] + F.in[15][l * NE + e]; }
;         }
;         __syncthreads();
;         if (w == 0) {
;             const int row = chunk * 64 + lane;
;             float v[32];
; #pragma unroll
;             for (int e = 0; e < 32; ++e) v[e] = lg[lane * 33 + e];
;             float tv[4]; int ti[4];
; #pragma unroll
;             for (int r = 0; r < 4; ++r) { float bv = v[0]; int bi = 0;
; #pragma unroll
;                 for (int e = 1; e < 32; ++e) { const bool tk = v[e] > bv; bv = tk ? v[e] : bv; bi = tk ? e : bi; }
	ds_read_b128 v[46:49], v42 offset:49152
	ds_read_b128 v[78:81], v43 offset:49152
	v_xor_b32_e32 v44, 16, v42
	v_xor_b32_e32 v45, 16, v43
	ds_read_b128 v[50:53], v44 offset:49152
	ds_read_b128 v[82:85], v45 offset:49152
	v_xor_b32_e32 v44, 32, v42
	v_xor_b32_e32 v45, 32, v43
	ds_read_b128 v[54:57], v44 offset:49152
	ds_read_b128 v[86:89], v45 offset:49152
	v_xor_b32_e32 v44, 48, v42
	v_xor_b32_e32 v45, 48, v43
	ds_read_b128 v[58:61], v44 offset:49152
	ds_read_b128 v[90:93], v45 offset:49152
	v_xor_b32_e32 v44, 64, v42
	v_xor_b32_e32 v45, 64, v43
	ds_read_b128 v[62:65], v44 offset:49152
	ds_read_b128 v[94:97], v45 offset:49152
	v_xor_b32_e32 v44, 0x50, v42
	v_xor_b32_e32 v45, 0x50, v43
	ds_read_b128 v[66:69], v44 offset:49152
	ds_read_b128 v[98:101], v45 offset:49152
	v_xor_b32_e32 v44, 0x60, v42
	v_xor_b32_e32 v45, 0x60, v43
	ds_read_b128 v[70:73], v44 offset:49152
	ds_read_b128 v[102:105], v45 offset:49152
	v_xor_b32_e32 v44, 0x70, v42
	v_xor_b32_e32 v45, 0x70, v43
	ds_read_b128 v[74:77], v44 offset:49152
	ds_read_b128 v[106:109], v45 offset:49152
	s_waitcnt lgkmcnt(14)
	v_mfma_f32_16x16x4_f32 v[18:21], v78, v46, v[18:21]
	v_mfma_f32_16x16x4_f32 v[18:21], v79, v47, v[18:21]
	v_mfma_f32_16x16x4_f32 v[18:21], v80, v48, v[18:21]
	v_mfma_f32_16x16x4_f32 v[18:21], v81, v49, v[18:21]
	s_waitcnt lgkmcnt(12)
	v_mfma_f32_16x16x4_f32 v[18:21], v82, v50, v[18:21]
	v_mfma_f32_16x16x4_f32 v[18:21], v83, v51, v[18:21]
	v_mfma_f32_16x16x4_f32 v[18:21], v84, v52, v[18:21]
	v_mfma_f32_16x16x4_f32 v[18:21], v85, v53, v[18:21]
	s_waitcnt lgkmcnt(10)
	v_mfma_f32_16x16x4_f32 v[18:21], v86, v54, v[18:21]
	v_mfma_f32_16x16x4_f32 v[18:21], v87, v55, v[18:21]
	v_mfma_f32_16x16x4_f32 v[18:21], v88, v56, v[18:21]
	v_mfma_f32_16x16x4_f32 v[18:21], v89, v57, v[18:21]
	s_waitcnt lgkmcnt(8)
	v_mfma_f32_16x16x4_f32 v[18:21], v90, v58, v[18:21]
	v_mfma_f32_16x16x4_f32 v[18:21], v91, v59, v[18:21]
	v_mfma_f32_16x16x4_f32 v[18:21], v92, v60, v[18:21]
	v_mfma_f32_16x16x4_f32 v[18:21], v93, v61, v[18:21]
	s_waitcnt lgkmcnt(6)
	v_mfma_f32_16x16x4_f32 v[18:21], v94, v62, v[18:21]
	v_mfma_f32_16x16x4_f32 v[18:21], v95, v63, v[18:21]
	v_mfma_f32_16x16x4_f32 v[18:21], v96, v64, v[18:21]
	v_mfma_f32_16x16x4_f32 v[18:21], v97, v65, v[18:21]
	s_waitcnt lgkmcnt(4)
	v_mfma_f32_16x16x4_f32 v[18:21], v98, v66, v[18:21]
	v_mfma_f32_16x16x4_f32 v[18:21], v99, v67, v[18:21]
	v_mfma_f32_16x16x4_f32 v[18:21], v100, v68, v[18:21]
	v_mfma_f32_16x16x4_f32 v[18:21], v101, v69, v[18:21]
	s_waitcnt lgkmcnt(2)
	v_mfma_f32_16x16x4_f32 v[18:21], v102, v70, v[18:21]
	v_mfma_f32_16x16x4_f32 v[18:21], v103, v71, v[18:21]
	v_mfma_f32_16x16x4_f32 v[18:21], v104, v72, v[18:21]
	v_mfma_f32_16x16x4_f32 v[18:21], v105, v73, v[18:21]
	s_waitcnt lgkmcnt(0)
	v_mfma_f32_16x16x4_f32 v[18:21], v106, v74, v[18:21]
	v_mfma_f32_16x16x4_f32 v[18:21], v107, v75, v[18:21]
	v_mfma_f32_16x16x4_f32 v[18:21], v108, v76, v[18:21]
	v_mfma_f32_16x16x4_f32 v[18:21], v109, v77, v[18:21]
	global_load_dwordx4 v[22:25], v[130:131], off
	s_and_b64 vcc, exec, s[52:53]
	s_waitcnt vmcnt(0)
	s_nop 5
	v_pk_add_f32 v[18:19], v[18:19], v[22:23]
	ds_write2_b32 v155, v18, v19 offset1:1
	v_pk_add_f32 v[18:19], v[20:21], v[24:25]
	ds_write2_b32 v155, v18, v19 offset0:2 offset1:3
	s_waitcnt lgkmcnt(0)
	s_barrier
	s_cbranch_vccz .LBB0_2134
	ds_read2_b32 v[22:23], v154 offset0:8 offset1:9
	ds_read2_b32 v[26:27], v154 offset0:10 offset1:11
	ds_read2_b32 v[28:29], v154 offset0:12 offset1:13
	ds_read2_b32 v[30:31], v154 offset0:14 offset1:15
	ds_read2_b32 v[32:33], v154 offset0:16 offset1:17
	ds_read2_b32 v[34:35], v154 offset0:18 offset1:19
	ds_read2_b32 v[36:37], v154 offset0:20 offset1:21
	ds_read2_b32 v[38:39], v154 offset0:22 offset1:23
	ds_read2_b32 v[40:41], v154 offset0:2 offset1:3
	ds_read2_b32 v[42:43], v154 offset0:4 offset1:5
	ds_read2_b32 v[44:45], v154 offset0:6 offset1:7
	ds_read2_b32 v[46:47], v154 offset1:1
	ds_read2_b32 v[48:49], v154 offset0:24 offset1:25
	ds_read2_b32 v[50:51], v154 offset0:26 offset1:27
	ds_read2_b32 v[52:53], v154 offset0:28 offset1:29
	ds_read2_b32 v[20:21], v154 offset0:30 offset1:31
	s_waitcnt lgkmcnt(4)
	v_cmp_gt_f32_e32 vcc, v47, v46
	v_mov_b32_e32 v25, 0
	s_nop 0
	v_cndmask_b32_e32 v19, v46, v47, vcc
	v_cndmask_b32_e64 v18, 0, 1, vcc
	v_cmp_gt_f32_e32 vcc, v40, v19
	s_nop 1
	v_cndmask_b32_e32 v19, v19, v40, vcc
	v_cndmask_b32_e64 v18, v18, 2, vcc
	v_cmp_gt_f32_e32 vcc, v41, v19
	s_nop 1
	v_cndmask_b32_e32 v19, v19, v41, vcc
	v_cndmask_b32_e64 v18, v18, 3, vcc
	v_cmp_gt_f32_e32 vcc, v42, v19
	s_nop 1
	v_cndmask_b32_e32 v19, v19, v42, vcc
	v_cndmask_b32_e64 v18, v18, 4, vcc
	v_cmp_gt_f32_e32 vcc, v43, v19
	s_nop 1
	v_cndmask_b32_e32 v19, v19, v43, vcc
	v_cndmask_b32_e64 v18, v18, 5, vcc
	v_cmp_gt_f32_e32 vcc, v44, v19
	s_nop 1
	v_cndmask_b32_e32 v19, v19, v44, vcc
	v_cndmask_b32_e64 v18, v18, 6, vcc
	v_cmp_gt_f32_e32 vcc, v45, v19
	s_nop 1
	v_cndmask_b32_e32 v19, v19, v45, vcc
	v_cndmask_b32_e64 v18, v18, 7, vcc
	v_cmp_gt_f32_e32 vcc, v22, v19
	s_nop 1
	v_cndmask_b32_e32 v19, v19, v22, vcc
	v_cndmask_b32_e64 v18, v18, 8, vcc
	v_cmp_gt_f32_e32 vcc, v23, v19
	s_nop 1
	v_cndmask_b32_e32 v19, v19, v23, vcc
	v_cndmask_b32_e64 v18, v18, 9, vcc
	v_cmp_gt_f32_e32 vcc, v26, v19
	s_nop 1
	v_cndmask_b32_e32 v19, v19, v26, vcc
	v_cndmask_b32_e64 v18, v18, 10, vcc
	v_cmp_gt_f32_e32 vcc, v27, v19
	s_nop 1
	v_cndmask_b32_e32 v19, v19, v27, vcc
	v_cndmask_b32_e64 v18, v18, 11, vcc
	v_cmp_gt_f32_e32 vcc, v28, v19
	s_nop 1
	v_cndmask_b32_e32 v19, v19, v28, vcc
	v_cndmask_b32_e64 v18, v18, 12, vcc
	v_cmp_gt_f32_e32 vcc, v29, v19
	s_nop 1
	v_cndmask_b32_e32 v19, v19, v29, vcc
	v_cndmask_b32_e64 v18, v18, 13, vcc
	v_cmp_gt_f32_e32 vcc, v30, v19
	s_nop 1
	v_cndmask_b32_e32 v19, v19, v30, vcc
	v_cndmask_b32_e64 v18, v18, 14, vcc
	v_cmp_gt_f32_e32 vcc, v31, v19
	s_nop 1
	v_cndmask_b32_e32 v19, v19, v31, vcc
	v_cndmask_b32_e64 v18, v18, 15, vcc
	v_cmp_gt_f32_e32 vcc, v32, v19
	s_nop 1
	v_cndmask_b32_e32 v19, v19, v32, vcc
	v_cndmask_b32_e64 v18, v18, 16, vcc
	v_cmp_gt_f32_e32 vcc, v33, v19
	s_nop 1
	v_cndmask_b32_e32 v19, v19, v33, vcc
	v_cndmask_b32_e64 v18, v18, 17, vcc
	v_cmp_gt_f32_e32 vcc, v34, v19
	s_nop 1
	v_cndmask_b32_e32 v19, v19, v34, vcc
	v_cndmask_b32_e64 v18, v18, 18, vcc
	v_cmp_gt_f32_e32 vcc, v35, v19
	s_nop 1
	v_cndmask_b32_e32 v19, v19, v35, vcc
	v_cndmask_b32_e64 v18, v18, 19, vcc
	v_cmp_gt_f32_e32 vcc, v36, v19
	s_nop 1
	v_cndmask_b32_e32 v19, v19, v36, vcc
	v_cndmask_b32_e64 v18, v18, 20, vcc
	v_cmp_gt_f32_e32 vcc, v37, v19
	s_nop 1
	v_cndmask_b32_e32 v19, v19, v37, vcc
	v_cndmask_b32_e64 v18, v18, 21, vcc
	v_cmp_gt_f32_e32 vcc, v38, v19
	s_nop 1
	v_cndmask_b32_e32 v19, v19, v38, vcc
	v_cndmask_b32_e64 v18, v18, 22, vcc
	v_cmp_gt_f32_e32 vcc, v39, v19
	s_nop 1
	v_cndmask_b32_e32 v19, v19, v39, vcc
	v_cndmask_b32_e64 v18, v18, 23, vcc
	s_waitcnt lgkmcnt(3)
; __device__ __forceinline__ void phase_row1(const Frame& F, int l) {
;     ...
; #pragma unroll
;             for (int r = 0; r < 4; ++r) { float bv = v[0]; int bi = 0;
; #pragma unroll
;                 for (int e = 1; e < 32; ++e) { const bool tk = v[e] > bv; bv = tk ? v[e] : bv; bi = tk ? e : bi; }
;                 tv[r] = bv; ti[r] = bi;
; #pragma unroll
;                 for (int e = 0; e < 32; ++e) v[e] = (e == bi) ? -INFINITY : v[e]; }
	v_cmp_gt_f32_e32 vcc, v48, v19
	s_nop 1
	v_cndmask_b32_e32 v19, v19, v48, vcc
	v_cndmask_b32_e64 v18, v18, 24, vcc
	v_cmp_gt_f32_e32 vcc, v49, v19
	s_nop 1
	v_cndmask_b32_e32 v19, v19, v49, vcc
	v_cndmask_b32_e64 v18, v18, 25, vcc
	s_waitcnt lgkmcnt(2)
	v_cmp_gt_f32_e32 vcc, v50, v19
	s_nop 1
	v_cndmask_b32_e32 v19, v19, v50, vcc
	v_cndmask_b32_e64 v18, v18, 26, vcc
	v_cmp_gt_f32_e32 vcc, v51, v19
	s_nop 1
	v_cndmask_b32_e32 v19, v19, v51, vcc
	v_cndmask_b32_e64 v18, v18, 27, vcc
	s_waitcnt lgkmcnt(1)
	v_cmp_gt_f32_e32 vcc, v52, v19
	s_nop 1
	v_cndmask_b32_e32 v19, v19, v52, vcc
	v_cndmask_b32_e64 v18, v18, 28, vcc
	v_cmp_gt_f32_e32 vcc, v53, v19
	s_nop 1
	v_cndmask_b32_e32 v19, v19, v53, vcc
	v_cndmask_b32_e64 v18, v18, 29, vcc
	s_waitcnt lgkmcnt(0)
	v_cmp_gt_f32_e32 vcc, v20, v19
	s_nop 1
	v_cndmask_b32_e32 v19, v19, v20, vcc
	v_cndmask_b32_e64 v18, v18, 30, vcc
	v_cmp_gt_f32_e32 vcc, v21, v19
	s_nop 1
	v_cndmask_b32_e64 v18, v18, 31, vcc
	v_cmp_ne_u32_e64 s[44:45], 0, v18
	s_nop 1
	v_cndmask_b32_e64 v24, v237, v46, s[44:45]
	v_cmp_ne_u32_e64 s[44:45], 1, v18
	s_nop 1
	v_cndmask_b32_e64 v46, v237, v47, s[44:45]
	v_cmp_ne_u32_e64 s[44:45], 2, v18
	s_nop 1
	v_cndmask_b32_e64 v40, v237, v40, s[44:45]
	v_cmp_ne_u32_e64 s[44:45], 3, v18
	s_nop 1
	v_cndmask_b32_e64 v41, v237, v41, s[44:45]
	v_cmp_ne_u32_e64 s[44:45], 4, v18
	s_nop 1
	v_cndmask_b32_e64 v42, v237, v42, s[44:45]
	v_cmp_ne_u32_e64 s[44:45], 5, v18
	s_nop 1
	v_cndmask_b32_e64 v43, v237, v43, s[44:45]
	v_cmp_ne_u32_e64 s[44:45], 6, v18
	s_nop 1
	v_cndmask_b32_e64 v44, v237, v44, s[44:45]
	v_cmp_ne_u32_e64 s[44:45], 7, v18
	s_nop 1
	v_cndmask_b32_e64 v45, v237, v45, s[44:45]
	v_cmp_ne_u32_e64 s[44:45], 8, v18
	s_nop 1
	v_cndmask_b32_e64 v22, v237, v22, s[44:45]
	v_cmp_ne_u32_e64 s[44:45], 9, v18
	s_nop 1
	v_cndmask_b32_e64 v47, v237, v23, s[44:45]
	v_cmp_ne_u32_e64 s[44:45], 10, v18
	s_nop 1
	v_cndmask_b32_e64 v26, v237, v26, s[44:45]
	v_cmp_ne_u32_e64 s[44:45], 11, v18
	s_nop 1
	v_cndmask_b32_e64 v54, v237, v27, s[44:45]
	v_cmp_ne_u32_e64 s[44:45], 12, v18
	s_nop 1
	v_cndmask_b32_e64 v28, v237, v28, s[44:45]
	v_cmp_ne_u32_e64 s[44:45], 13, v18
	s_nop 1
	v_cndmask_b32_e64 v29, v237, v29, s[44:45]
	v_cmp_ne_u32_e64 s[44:45], 14, v18
	s_nop 1
	v_cndmask_b32_e64 v30, v237, v30, s[44:45]
	v_cmp_ne_u32_e64 s[44:45], 15, v18
	s_nop 1
	v_cndmask_b32_e64 v31, v237, v31, s[44:45]
	v_cmp_ne_u32_e64 s[44:45], 16, v18
	s_nop 1
	v_cndmask_b32_e64 v32, v237, v32, s[44:45]
	v_cmp_ne_u32_e64 s[44:45], 17, v18
	s_nop 1
	v_cndmask_b32_e64 v33, v237, v33, s[44:45]
	v_cmp_ne_u32_e64 s[44:45], 18, v18
	s_nop 1
	v_cndmask_b32_e64 v34, v237, v34, s[44:45]
	v_cmp_ne_u32_e64 s[44:45], 19, v18
	s_nop 1
	v_cndmask_b32_e64 v35, v237, v35, s[44:45]
	v_cmp_ne_u32_e64 s[44:45], 20, v18
	s_nop 1
	v_cndmask_b32_e64 v36, v237, v36, s[44:45]
	v_cmp_ne_u32_e64 s[44:45], 21, v18
	s_nop 1
	v_cndmask_b32_e64 v37, v237, v37, s[44:45]
	v_cmp_ne_u32_e64 s[44:45], 22, v18
	s_nop 1
	v_cndmask_b32_e64 v38, v237, v38, s[44:45]
	v_cmp_ne_u32_e64 s[44:45], 23, v18
	s_nop 1
	v_cndmask_b32_e64 v39, v237, v39, s[44:45]
	v_cmp_ne_u32_e64 s[44:45], 24, v18
	s_nop 1
	v_cndmask_b32_e64 v48, v237, v48, s[44:45]
	v_cmp_ne_u32_e64 s[44:45], 25, v18
	s_nop 1
	v_cndmask_b32_e64 v49, v237, v49, s[44:45]
	v_cmp_ne_u32_e64 s[44:45], 26, v18
	s_nop 1
	v_cndmask_b32_e64 v50, v237, v50, s[44:45]
	v_cmp_ne_u32_e64 s[44:45], 27, v18
	s_nop 1
	v_cndmask_b32_e64 v51, v237, v51, s[44:45]
	v_cmp_ne_u32_e64 s[44:45], 28, v18
	s_nop 1
	v_cndmask_b32_e64 v52, v237, v52, s[44:45]
	v_cmp_ne_u32_e64 s[44:45], 29, v18
	s_nop 1
	v_cndmask_b32_e64 v53, v237, v53, s[44:45]
	v_cmp_ne_u32_e64 s[44:45], 30, v18
	s_nop 1
	v_cndmask_b32_e64 v55, v237, v20, s[44:45]
	v_cmp_ne_u32_e64 s[44:45], 31, v18
	s_nop 1
	v_cndmask_b32_e64 v23, v237, v21, s[44:45]
	v_cmp_gt_f32_e64 s[44:45], v46, v24
	s_nop 1
	v_cndmask_b32_e64 v27, v24, v46, s[44:45]
	v_cndmask_b32_e64 v20, 0, 1, s[44:45]
	v_cmp_gt_f32_e64 s[44:45], v40, v27
	s_nop 1
	v_cndmask_b32_e64 v27, v27, v40, s[44:45]
	v_cndmask_b32_e64 v20, v20, 2, s[44:45]
	v_cmp_gt_f32_e64 s[44:45], v41, v27
	s_nop 1
	v_cndmask_b32_e64 v27, v27, v41, s[44:45]
	v_cndmask_b32_e64 v20, v20, 3, s[44:45]
	v_cmp_gt_f32_e64 s[44:45], v42, v27
	s_nop 1
	v_cndmask_b32_e64 v27, v27, v42, s[44:45]
	v_cndmask_b32_e64 v20, v20, 4, s[44:45]
	v_cmp_gt_f32_e64 s[44:45], v43, v27
	s_nop 1
	v_cndmask_b32_e64 v27, v27, v43, s[44:45]
	v_cndmask_b32_e64 v20, v20, 5, s[44:45]
	v_cmp_gt_f32_e64 s[44:45], v44, v27
	s_nop 1
	v_cndmask_b32_e64 v27, v27, v44, s[44:45]
	v_cndmask_b32_e64 v20, v20, 6, s[44:45]
	v_cmp_gt_f32_e64 s[44:45], v45, v27
	s_nop 1
	v_cndmask_b32_e64 v27, v27, v45, s[44:45]
	v_cndmask_b32_e64 v20, v20, 7, s[44:45]
	v_cmp_gt_f32_e64 s[44:45], v22, v27
	s_nop 1
	v_cndmask_b32_e64 v27, v27, v22, s[44:45]
	v_cndmask_b32_e64 v20, v20, 8, s[44:45]
	v_cmp_gt_f32_e64 s[44:45], v47, v27
	s_nop 1
	v_cndmask_b32_e64 v27, v27, v47, s[44:45]
	v_cndmask_b32_e64 v20, v20, 9, s[44:45]
	v_cmp_gt_f32_e64 s[44:45], v26, v27
	s_nop 1
	v_cndmask_b32_e64 v27, v27, v26, s[44:45]
	v_cndmask_b32_e64 v20, v20, 10, s[44:45]
	v_cmp_gt_f32_e64 s[44:45], v54, v27
	s_nop 1
	v_cndmask_b32_e64 v27, v27, v54, s[44:45]
	v_cndmask_b32_e64 v20, v20, 11, s[44:45]
	v_cmp_gt_f32_e64 s[44:45], v28, v27
	s_nop 1
	v_cndmask_b32_e64 v27, v27, v28, s[44:45]
	v_cndmask_b32_e64 v20, v20, 12, s[44:45]
	v_cmp_gt_f32_e64 s[44:45], v29, v27
	s_nop 1
	v_cndmask_b32_e64 v27, v27, v29, s[44:45]
	v_cndmask_b32_e64 v20, v20, 13, s[44:45]
	v_cmp_gt_f32_e64 s[44:45], v30, v27
	s_nop 1
	v_cndmask_b32_e64 v27, v27, v30, s[44:45]
	v_cndmask_b32_e64 v20, v20, 14, s[44:45]
	v_cmp_gt_f32_e64 s[44:45], v31, v27
; __device__ __forceinline__ void phase_row1(const Frame& F, int l) {
;     ...
; #pragma unroll
;             for (int r = 0; r < 4; ++r) { float bv = v[0]; int bi = 0;
; #pragma unroll
;                 for (int e = 1; e < 32; ++e) { const bool tk = v[e] > bv; bv = tk ? v[e] : bv; bi = tk ? e : bi; }
;                 tv[r] = bv; ti[r] = bi;
; #pragma unroll
;                 for (int e = 0; e < 32; ++e) v[e] = (e == bi) ? -INFINITY : v[e]; }
	s_nop 1
	v_cndmask_b32_e64 v27, v27, v31, s[44:45]
	v_cndmask_b32_e64 v20, v20, 15, s[44:45]
	v_cmp_gt_f32_e64 s[44:45], v32, v27
	s_nop 1
	v_cndmask_b32_e64 v27, v27, v32, s[44:45]
	v_cndmask_b32_e64 v20, v20, 16, s[44:45]
	v_cmp_gt_f32_e64 s[44:45], v33, v27
	s_nop 1
	v_cndmask_b32_e64 v27, v27, v33, s[44:45]
	v_cndmask_b32_e64 v20, v20, 17, s[44:45]
	v_cmp_gt_f32_e64 s[44:45], v34, v27
	s_nop 1
	v_cndmask_b32_e64 v27, v27, v34, s[44:45]
	v_cndmask_b32_e64 v20, v20, 18, s[44:45]
	v_cmp_gt_f32_e64 s[44:45], v35, v27
	s_nop 1
	v_cndmask_b32_e64 v27, v27, v35, s[44:45]
	v_cndmask_b32_e64 v20, v20, 19, s[44:45]
	v_cmp_gt_f32_e64 s[44:45], v36, v27
	s_nop 1
	v_cndmask_b32_e64 v27, v27, v36, s[44:45]
	v_cndmask_b32_e64 v20, v20, 20, s[44:45]
	v_cmp_gt_f32_e64 s[44:45], v37, v27
	s_nop 1
	v_cndmask_b32_e64 v27, v27, v37, s[44:45]
	v_cndmask_b32_e64 v20, v20, 21, s[44:45]
	v_cmp_gt_f32_e64 s[44:45], v38, v27
	s_nop 1
	v_cndmask_b32_e64 v27, v27, v38, s[44:45]
	v_cndmask_b32_e64 v20, v20, 22, s[44:45]
	v_cmp_gt_f32_e64 s[44:45], v39, v27
	s_nop 1
	v_cndmask_b32_e64 v27, v27, v39, s[44:45]
	v_cndmask_b32_e64 v20, v20, 23, s[44:45]
	v_cmp_gt_f32_e64 s[44:45], v48, v27
	s_nop 1
	v_cndmask_b32_e64 v27, v27, v48, s[44:45]
	v_cndmask_b32_e64 v20, v20, 24, s[44:45]
	v_cmp_gt_f32_e64 s[44:45], v49, v27
	s_nop 1
	v_cndmask_b32_e64 v27, v27, v49, s[44:45]
	v_cndmask_b32_e64 v20, v20, 25, s[44:45]
	v_cmp_gt_f32_e64 s[44:45], v50, v27
	s_nop 1
	v_cndmask_b32_e64 v27, v27, v50, s[44:45]
	v_cndmask_b32_e64 v20, v20, 26, s[44:45]
	v_cmp_gt_f32_e64 s[44:45], v51, v27
	s_nop 1
	v_cndmask_b32_e64 v27, v27, v51, s[44:45]
	v_cndmask_b32_e64 v20, v20, 27, s[44:45]
	v_cmp_gt_f32_e64 s[44:45], v52, v27
	s_nop 1
	v_cndmask_b32_e64 v27, v27, v52, s[44:45]
	v_cndmask_b32_e64 v20, v20, 28, s[44:45]
	v_cmp_gt_f32_e64 s[44:45], v53, v27
	s_nop 1
	v_cndmask_b32_e64 v27, v27, v53, s[44:45]
	v_cndmask_b32_e64 v20, v20, 29, s[44:45]
	v_cmp_gt_f32_e64 s[44:45], v55, v27
	s_nop 1
	v_cndmask_b32_e64 v27, v27, v55, s[44:45]
	v_cndmask_b32_e64 v20, v20, 30, s[44:45]
	v_cmp_gt_f32_e64 s[44:45], v23, v27
	s_nop 1
	v_cndmask_b32_e64 v20, v20, 31, s[44:45]
	v_cmp_ne_u32_e64 s[46:47], 0, v20
	s_nop 1
	v_cndmask_b32_e64 v24, v237, v24, s[46:47]
	v_cmp_ne_u32_e64 s[46:47], 1, v20
	s_nop 1
	v_cndmask_b32_e64 v46, v237, v46, s[46:47]
	v_cmp_ne_u32_e64 s[46:47], 2, v20
	s_nop 1
	v_cndmask_b32_e64 v40, v237, v40, s[46:47]
	v_cmp_ne_u32_e64 s[46:47], 3, v20
	s_nop 1
	v_cndmask_b32_e64 v41, v237, v41, s[46:47]
	v_cmp_ne_u32_e64 s[46:47], 4, v20
	s_nop 1
	v_cndmask_b32_e64 v42, v237, v42, s[46:47]
	v_cmp_ne_u32_e64 s[46:47], 5, v20
	s_nop 1
	v_cndmask_b32_e64 v43, v237, v43, s[46:47]
	v_cmp_ne_u32_e64 s[46:47], 6, v20
	s_nop 1
	v_cndmask_b32_e64 v44, v237, v44, s[46:47]
	v_cmp_ne_u32_e64 s[46:47], 7, v20
	s_nop 1
	v_cndmask_b32_e64 v45, v237, v45, s[46:47]
	v_cmp_ne_u32_e64 s[46:47], 8, v20
	s_nop 1
	v_cndmask_b32_e64 v56, v237, v22, s[46:47]
	v_cmp_ne_u32_e64 s[46:47], 9, v20
	s_nop 1
	v_cndmask_b32_e64 v47, v237, v47, s[46:47]
	v_cmp_ne_u32_e64 s[46:47], 10, v20
	s_nop 1
	v_cndmask_b32_e64 v26, v237, v26, s[46:47]
	v_cmp_ne_u32_e64 s[46:47], 11, v20
	s_nop 1
	v_cndmask_b32_e64 v54, v237, v54, s[46:47]
	v_cmp_ne_u32_e64 s[46:47], 12, v20
	s_nop 1
	v_cndmask_b32_e64 v28, v237, v28, s[46:47]
	v_cmp_ne_u32_e64 s[46:47], 13, v20
	s_nop 1
	v_cndmask_b32_e64 v57, v237, v29, s[46:47]
	v_cmp_ne_u32_e64 s[46:47], 14, v20
	s_nop 1
	v_cndmask_b32_e64 v30, v237, v30, s[46:47]
	v_cmp_ne_u32_e64 s[46:47], 15, v20
	s_nop 1
	v_cndmask_b32_e64 v58, v237, v31, s[46:47]
	v_cmp_ne_u32_e64 s[46:47], 16, v20
	s_nop 1
	v_cndmask_b32_e64 v32, v237, v32, s[46:47]
	v_cmp_ne_u32_e64 s[46:47], 17, v20
	s_nop 1
	v_cndmask_b32_e64 v33, v237, v33, s[46:47]
	v_cmp_ne_u32_e64 s[46:47], 18, v20
	s_nop 1
	v_cndmask_b32_e64 v34, v237, v34, s[46:47]
	v_cmp_ne_u32_e64 s[46:47], 19, v20
	s_nop 1
	v_cndmask_b32_e64 v35, v237, v35, s[46:47]
	v_cmp_ne_u32_e64 s[46:47], 20, v20
	s_nop 1
	v_cndmask_b32_e64 v36, v237, v36, s[46:47]
	v_cmp_ne_u32_e64 s[46:47], 21, v20
	s_nop 1
	v_cndmask_b32_e64 v37, v237, v37, s[46:47]
	v_cmp_ne_u32_e64 s[46:47], 22, v20
	s_nop 1
	v_cndmask_b32_e64 v38, v237, v38, s[46:47]
	v_cmp_ne_u32_e64 s[46:47], 23, v20
	s_nop 1
	v_cndmask_b32_e64 v39, v237, v39, s[46:47]
	v_cmp_ne_u32_e64 s[46:47], 24, v20
	s_nop 1
	v_cndmask_b32_e64 v48, v237, v48, s[46:47]
	v_cmp_ne_u32_e64 s[46:47], 25, v20
	s_nop 1
	v_cndmask_b32_e64 v49, v237, v49, s[46:47]
	v_cmp_ne_u32_e64 s[46:47], 26, v20
	s_nop 1
	v_cndmask_b32_e64 v50, v237, v50, s[46:47]
	v_cmp_ne_u32_e64 s[46:47], 27, v20
	s_nop 1
	v_cndmask_b32_e64 v51, v237, v51, s[46:47]
	v_cmp_ne_u32_e64 s[46:47], 28, v20
	s_nop 1
	v_cndmask_b32_e64 v52, v237, v52, s[46:47]
	v_cmp_ne_u32_e64 s[46:47], 29, v20
	s_nop 1
	v_cndmask_b32_e64 v53, v237, v53, s[46:47]
	v_cmp_ne_u32_e64 s[46:47], 30, v20
	s_nop 1
	v_cndmask_b32_e64 v55, v237, v55, s[46:47]
	v_cmp_ne_u32_e64 s[46:47], 31, v20
	s_nop 1
	v_cndmask_b32_e64 v29, v237, v23, s[46:47]
	v_cmp_gt_f32_e64 s[46:47], v46, v24
	s_nop 1
	v_cndmask_b32_e64 v31, v24, v46, s[46:47]
	v_cndmask_b32_e64 v22, 0, 1, s[46:47]
	v_cmp_gt_f32_e64 s[46:47], v40, v31
	s_nop 1
	v_cndmask_b32_e64 v31, v31, v40, s[46:47]
	v_cndmask_b32_e64 v22, v22, 2, s[46:47]
	v_cmp_gt_f32_e64 s[46:47], v41, v31
	s_nop 1
	v_cndmask_b32_e64 v31, v31, v41, s[46:47]
	v_cndmask_b32_e64 v22, v22, 3, s[46:47]
	v_cmp_gt_f32_e64 s[46:47], v42, v31
	s_nop 1
	v_cndmask_b32_e64 v31, v31, v42, s[46:47]
	v_cndmask_b32_e64 v22, v22, 4, s[46:47]
	v_cmp_gt_f32_e64 s[46:47], v43, v31
	s_nop 1
	v_cndmask_b32_e64 v31, v31, v43, s[46:47]
	v_cndmask_b32_e64 v22, v22, 5, s[46:47]
; __device__ __forceinline__ void phase_row1(const Frame& F, int l) {
;     ...
; #pragma unroll
;             for (int r = 0; r < 4; ++r) { float bv = v[0]; int bi = 0;
; #pragma unroll
;                 for (int e = 1; e < 32; ++e) { const bool tk = v[e] > bv; bv = tk ? v[e] : bv; bi = tk ? e : bi; }
;                 tv[r] = bv; ti[r] = bi;
; #pragma unroll
;                 for (int e = 0; e < 32; ++e) v[e] = (e == bi) ? -INFINITY : v[e]; }
	v_cmp_gt_f32_e64 s[46:47], v44, v31
	s_nop 1
	v_cndmask_b32_e64 v31, v31, v44, s[46:47]
	v_cndmask_b32_e64 v22, v22, 6, s[46:47]
	v_cmp_gt_f32_e64 s[46:47], v45, v31
	s_nop 1
	v_cndmask_b32_e64 v31, v31, v45, s[46:47]
	v_cndmask_b32_e64 v22, v22, 7, s[46:47]
	v_cmp_gt_f32_e64 s[46:47], v56, v31
	s_nop 1
	v_cndmask_b32_e64 v31, v31, v56, s[46:47]
	v_cndmask_b32_e64 v22, v22, 8, s[46:47]
	v_cmp_gt_f32_e64 s[46:47], v47, v31
	s_nop 1
	v_cndmask_b32_e64 v31, v31, v47, s[46:47]
	v_cndmask_b32_e64 v22, v22, 9, s[46:47]
	v_cmp_gt_f32_e64 s[46:47], v26, v31
	s_nop 1
	v_cndmask_b32_e64 v31, v31, v26, s[46:47]
	v_cndmask_b32_e64 v22, v22, 10, s[46:47]
	v_cmp_gt_f32_e64 s[46:47], v54, v31
	s_nop 1
	v_cndmask_b32_e64 v31, v31, v54, s[46:47]
	v_cndmask_b32_e64 v22, v22, 11, s[46:47]
	v_cmp_gt_f32_e64 s[46:47], v28, v31
	s_nop 1
	v_cndmask_b32_e64 v31, v31, v28, s[46:47]
	v_cndmask_b32_e64 v22, v22, 12, s[46:47]
	v_cmp_gt_f32_e64 s[46:47], v57, v31
	s_nop 1
	v_cndmask_b32_e64 v31, v31, v57, s[46:47]
	v_cndmask_b32_e64 v22, v22, 13, s[46:47]
	v_cmp_gt_f32_e64 s[46:47], v30, v31
	s_nop 1
	v_cndmask_b32_e64 v31, v31, v30, s[46:47]
	v_cndmask_b32_e64 v22, v22, 14, s[46:47]
	v_cmp_gt_f32_e64 s[46:47], v58, v31
	s_nop 1
	v_cndmask_b32_e64 v31, v31, v58, s[46:47]
	v_cndmask_b32_e64 v22, v22, 15, s[46:47]
	v_cmp_gt_f32_e64 s[46:47], v32, v31
	s_nop 1
	v_cndmask_b32_e64 v31, v31, v32, s[46:47]
	v_cndmask_b32_e64 v22, v22, 16, s[46:47]
	v_cmp_gt_f32_e64 s[46:47], v33, v31
	s_nop 1
	v_cndmask_b32_e64 v31, v31, v33, s[46:47]
	v_cndmask_b32_e64 v22, v22, 17, s[46:47]
	v_cmp_gt_f32_e64 s[46:47], v34, v31
	s_nop 1
	v_cndmask_b32_e64 v31, v31, v34, s[46:47]
	v_cndmask_b32_e64 v22, v22, 18, s[46:47]
	v_cmp_gt_f32_e64 s[46:47], v35, v31
	s_nop 1
	v_cndmask_b32_e64 v31, v31, v35, s[46:47]
	v_cndmask_b32_e64 v22, v22, 19, s[46:47]
	v_cmp_gt_f32_e64 s[46:47], v36, v31
	s_nop 1
	v_cndmask_b32_e64 v31, v31, v36, s[46:47]
	v_cndmask_b32_e64 v22, v22, 20, s[46:47]
	v_cmp_gt_f32_e64 s[46:47], v37, v31
	s_nop 1
	v_cndmask_b32_e64 v31, v31, v37, s[46:47]
	v_cndmask_b32_e64 v22, v22, 21, s[46:47]
	v_cmp_gt_f32_e64 s[46:47], v38, v31
	s_nop 1
	v_cndmask_b32_e64 v31, v31, v38, s[46:47]
	v_cndmask_b32_e64 v22, v22, 22, s[46:47]
	v_cmp_gt_f32_e64 s[46:47], v39, v31
	s_nop 1
	v_cndmask_b32_e64 v31, v31, v39, s[46:47]
	v_cndmask_b32_e64 v22, v22, 23, s[46:47]
	v_cmp_gt_f32_e64 s[46:47], v48, v31
	s_nop 1
	v_cndmask_b32_e64 v31, v31, v48, s[46:47]
	v_cndmask_b32_e64 v22, v22, 24, s[46:47]
	v_cmp_gt_f32_e64 s[46:47], v49, v31
	s_nop 1
	v_cndmask_b32_e64 v31, v31, v49, s[46:47]
	v_cndmask_b32_e64 v22, v22, 25, s[46:47]
	v_cmp_gt_f32_e64 s[46:47], v50, v31
	s_nop 1
	v_cndmask_b32_e64 v31, v31, v50, s[46:47]
	v_cndmask_b32_e64 v22, v22, 26, s[46:47]
	v_cmp_gt_f32_e64 s[46:47], v51, v31
	s_nop 1
	v_cndmask_b32_e64 v31, v31, v51, s[46:47]
	v_cndmask_b32_e64 v22, v22, 27, s[46:47]
	v_cmp_gt_f32_e64 s[46:47], v52, v31
	s_nop 1
	v_cndmask_b32_e64 v31, v31, v52, s[46:47]
	v_cndmask_b32_e64 v22, v22, 28, s[46:47]
	v_cmp_gt_f32_e64 s[46:47], v53, v31
	s_nop 1
	v_cndmask_b32_e64 v31, v31, v53, s[46:47]
	v_cndmask_b32_e64 v22, v22, 29, s[46:47]
	v_cmp_gt_f32_e64 s[46:47], v55, v31
	s_nop 1
	v_cndmask_b32_e64 v31, v31, v55, s[46:47]
	v_cndmask_b32_e64 v22, v22, 30, s[46:47]
	v_cmp_gt_f32_e64 s[46:47], v29, v31
	s_nop 1
	v_cndmask_b32_e64 v22, v22, 31, s[46:47]
	v_cmp_ne_u32_e64 s[48:49], 0, v22
	s_nop 1
	v_cndmask_b32_e64 v24, v237, v24, s[48:49]
	v_cmp_ne_u32_e64 s[48:49], 1, v22
	s_nop 1
	v_cndmask_b32_e64 v46, v237, v46, s[48:49]
	v_cmp_ne_u32_e64 s[48:49], 2, v22
	s_nop 1
	v_cndmask_b32_e64 v40, v237, v40, s[48:49]
	v_cmp_ne_u32_e64 s[48:49], 3, v22
	s_nop 1
	v_cndmask_b32_e64 v41, v237, v41, s[48:49]
	v_cmp_ne_u32_e64 s[48:49], 4, v22
	s_nop 1
	v_cndmask_b32_e64 v42, v237, v42, s[48:49]
	v_cmp_ne_u32_e64 s[48:49], 5, v22
	s_nop 1
	v_cndmask_b32_e64 v43, v237, v43, s[48:49]
	v_cmp_ne_u32_e64 s[48:49], 6, v22
	s_nop 1
	v_cndmask_b32_e64 v44, v237, v44, s[48:49]
	v_cmp_ne_u32_e64 s[48:49], 7, v22
	s_nop 1
	v_cndmask_b32_e64 v45, v237, v45, s[48:49]
	v_cmp_ne_u32_e64 s[48:49], 8, v22
	s_nop 1
	v_cndmask_b32_e64 v56, v237, v56, s[48:49]
	v_cmp_ne_u32_e64 s[48:49], 9, v22
	s_nop 1
	v_cndmask_b32_e64 v47, v237, v47, s[48:49]
	v_cmp_ne_u32_e64 s[48:49], 10, v22
	s_nop 1
	v_cndmask_b32_e64 v26, v237, v26, s[48:49]
	v_cmp_ne_u32_e64 s[48:49], 11, v22
	s_nop 1
	v_cndmask_b32_e64 v54, v237, v54, s[48:49]
	v_cmp_ne_u32_e64 s[48:49], 12, v22
	s_nop 1
	v_cndmask_b32_e64 v28, v237, v28, s[48:49]
	v_cmp_ne_u32_e64 s[48:49], 13, v22
	s_nop 1
	v_cndmask_b32_e64 v57, v237, v57, s[48:49]
	v_cmp_ne_u32_e64 s[48:49], 14, v22
	s_nop 1
	v_cndmask_b32_e64 v30, v237, v30, s[48:49]
	v_cmp_ne_u32_e64 s[48:49], 15, v22
	s_nop 1
	v_cndmask_b32_e64 v58, v237, v58, s[48:49]
	v_cmp_ne_u32_e64 s[48:49], 16, v22
	s_nop 1
	v_cndmask_b32_e64 v59, v237, v32, s[48:49]
	v_cmp_ne_u32_e64 s[48:49], 17, v22
	s_nop 1
	v_cndmask_b32_e64 v60, v237, v33, s[48:49]
	v_cmp_ne_u32_e64 s[48:49], 18, v22
	s_nop 1
	v_cndmask_b32_e64 v34, v237, v34, s[48:49]
	v_cmp_ne_u32_e64 s[48:49], 19, v22
	s_nop 1
	v_cndmask_b32_e64 v61, v237, v35, s[48:49]
	v_cmp_ne_u32_e64 s[48:49], 20, v22
	s_nop 1
	v_cndmask_b32_e64 v62, v237, v36, s[48:49]
	v_cmp_ne_u32_e64 s[48:49], 21, v22
	s_nop 1
	v_cndmask_b32_e64 v63, v237, v37, s[48:49]
	v_cmp_ne_u32_e64 s[48:49], 22, v22
	s_nop 1
	v_cndmask_b32_e64 v38, v237, v38, s[48:49]
	v_cmp_ne_u32_e64 s[48:49], 23, v22
	s_nop 1
	v_cndmask_b32_e64 v39, v237, v39, s[48:49]
; #define LAS __attribute__((address_space(3)))
; #define LDS_WAIT() asm volatile("s_waitcnt lgkmcnt(0)" ::: "memory")
; __device__ __forceinline__ void phase_row1(const Frame& F, int l) {
;     ...
;             for (int r = 0; r < 4; ++r) { float bv = v[0]; int bi = 0;
; #pragma unroll
;                 for (int e = 1; e < 32; ++e) { const bool tk = v[e] > bv; bv = tk ? v[e] : bv; bi = tk ? e : bi; }
;                 tv[r] = bv; ti[r] = bi;
; #pragma unroll
;                 for (int e = 0; e < 32; ++e) v[e] = (e == bi) ? -INFINITY : v[e]; }
;             float ev[4], es = 0.f;
; #pragma unroll
;             for (int r = 0; r < 4; ++r) { ev[r] = expf(tv[r] - tv[0]); es += ev[r]; }
;             const float rowscale = ((const float*)(F.ws + WS_HS))[row];
;             int lp[4];
; #pragma unroll
;             for (int r = 0; r < 4; ++r) lp[r] = __hip_atomic_fetch_add((LAS int*)(F.lds + 16384) + ti[r], 1, __ATOMIC_RELAXED, __HIP_MEMORY_SCOPE_WORKGROUP);
;             LDS_WAIT();
;             int base = 0;
;             if (lane < 32) { const int c = lc[lane]; unsigned* cnt = (unsigned*)(F.ws + WS_CTL) + CW_CNT + l * NE; base = c > 0 ? (int)atomicAdd(cnt + lane, (unsigned)c) : 0; }
	v_cmp_ne_u32_e64 s[48:49], 24, v22
	s_nop 1
	v_cndmask_b32_e64 v48, v237, v48, s[48:49]
	v_cmp_ne_u32_e64 s[48:49], 25, v22
	s_nop 1
	v_cndmask_b32_e64 v49, v237, v49, s[48:49]
	v_cmp_ne_u32_e64 s[48:49], 26, v22
	s_nop 1
	v_cndmask_b32_e64 v50, v237, v50, s[48:49]
	v_cmp_ne_u32_e64 s[48:49], 27, v22
	s_nop 1
	v_cndmask_b32_e64 v51, v237, v51, s[48:49]
	v_cmp_ne_u32_e64 s[48:49], 28, v22
	s_nop 1
	v_cndmask_b32_e64 v52, v237, v52, s[48:49]
	v_cmp_ne_u32_e64 s[48:49], 29, v22
	s_nop 1
	v_cndmask_b32_e64 v53, v237, v53, s[48:49]
	v_cmp_ne_u32_e64 s[48:49], 30, v22
	s_nop 1
	v_cndmask_b32_e64 v55, v237, v55, s[48:49]
	v_cmp_ne_u32_e64 s[48:49], 31, v22
	s_nop 1
	v_cndmask_b32_e64 v35, v237, v29, s[48:49]
	v_cmp_gt_f32_e64 s[48:49], v46, v24
	s_nop 1
	v_cndmask_b32_e64 v24, v24, v46, s[48:49]
	v_cndmask_b32_e64 v32, 0, 1, s[48:49]
	v_cmp_gt_f32_e64 s[48:49], v40, v24
	s_nop 1
	v_cndmask_b32_e64 v24, v24, v40, s[48:49]
	v_cndmask_b32_e64 v32, v32, 2, s[48:49]
	v_cmp_gt_f32_e64 s[48:49], v41, v24
	s_nop 1
	v_cndmask_b32_e64 v24, v24, v41, s[48:49]
	v_cndmask_b32_e64 v32, v32, 3, s[48:49]
	v_cmp_gt_f32_e64 s[48:49], v42, v24
	s_nop 1
	v_cndmask_b32_e64 v24, v24, v42, s[48:49]
	v_cndmask_b32_e64 v32, v32, 4, s[48:49]
	v_cmp_gt_f32_e64 s[48:49], v43, v24
	s_nop 1
	v_cndmask_b32_e64 v24, v24, v43, s[48:49]
	v_cndmask_b32_e64 v32, v32, 5, s[48:49]
	v_cmp_gt_f32_e64 s[48:49], v44, v24
	s_nop 1
	v_cndmask_b32_e64 v24, v24, v44, s[48:49]
	v_cndmask_b32_e64 v32, v32, 6, s[48:49]
	v_cmp_gt_f32_e64 s[48:49], v45, v24
	s_nop 1
	v_cndmask_b32_e64 v24, v24, v45, s[48:49]
	v_cndmask_b32_e64 v32, v32, 7, s[48:49]
	v_cmp_gt_f32_e64 s[48:49], v56, v24
	s_nop 1
	v_cndmask_b32_e64 v40, v32, 8, s[48:49]
	v_or_b32_e32 v32, s3, v1
	v_ashrrev_i32_e32 v33, 31, v32
	v_lshl_add_u64 v[36:37], v[32:33], 2, s[54:55]
	global_load_dword v36, v[36:37], off
	v_cndmask_b32_e64 v24, v24, v56, s[48:49]
	v_cmp_gt_f32_e64 s[48:49], v47, v24
	s_nop 1
	v_cndmask_b32_e64 v24, v24, v47, s[48:49]
	v_cndmask_b32_e64 v33, v40, 9, s[48:49]
	v_cmp_gt_f32_e64 s[48:49], v26, v24
	s_nop 1
	v_cndmask_b32_e64 v24, v24, v26, s[48:49]
	v_cndmask_b32_e64 v33, v33, 10, s[48:49]
	v_cmp_gt_f32_e64 s[48:49], v54, v24
	s_nop 1
	v_cndmask_b32_e64 v24, v24, v54, s[48:49]
	v_cndmask_b32_e64 v26, v33, 11, s[48:49]
	v_cmp_gt_f32_e64 s[48:49], v28, v24
	s_nop 1
	v_cndmask_b32_e64 v24, v24, v28, s[48:49]
	v_cndmask_b32_e64 v26, v26, 12, s[48:49]
	v_cmp_gt_f32_e64 s[48:49], v57, v24
	s_nop 1
	v_cndmask_b32_e64 v24, v24, v57, s[48:49]
	v_cndmask_b32_e64 v26, v26, 13, s[48:49]
	v_cmp_gt_f32_e64 s[48:49], v30, v24
	s_nop 1
	v_cndmask_b32_e64 v24, v24, v30, s[48:49]
	v_cndmask_b32_e64 v26, v26, 14, s[48:49]
	v_cmp_gt_f32_e64 s[48:49], v58, v24
	s_nop 1
	v_cndmask_b32_e64 v24, v24, v58, s[48:49]
	v_cndmask_b32_e64 v26, v26, 15, s[48:49]
	v_cmp_gt_f32_e64 s[48:49], v59, v24
	s_nop 1
	v_cndmask_b32_e64 v24, v24, v59, s[48:49]
	v_cndmask_b32_e64 v26, v26, 16, s[48:49]
	v_cmp_gt_f32_e64 s[48:49], v60, v24
	s_nop 1
	v_cndmask_b32_e64 v24, v24, v60, s[48:49]
	v_cndmask_b32_e64 v26, v26, 17, s[48:49]
	v_cmp_gt_f32_e64 s[48:49], v34, v24
	s_nop 1
	v_cndmask_b32_e64 v24, v24, v34, s[48:49]
	v_cndmask_b32_e64 v26, v26, 18, s[48:49]
	v_cmp_gt_f32_e64 s[48:49], v61, v24
	s_nop 1
	v_cndmask_b32_e64 v24, v24, v61, s[48:49]
	v_cndmask_b32_e64 v26, v26, 19, s[48:49]
	v_cmp_gt_f32_e64 s[48:49], v62, v24
	s_nop 1
	v_cndmask_b32_e64 v24, v24, v62, s[48:49]
	v_cndmask_b32_e64 v26, v26, 20, s[48:49]
	v_cmp_gt_f32_e64 s[48:49], v63, v24
	s_nop 1
	v_cndmask_b32_e64 v24, v24, v63, s[48:49]
	v_cndmask_b32_e64 v26, v26, 21, s[48:49]
	v_cmp_gt_f32_e64 s[48:49], v38, v24
	s_nop 1
	v_cndmask_b32_e64 v24, v24, v38, s[48:49]
	v_cndmask_b32_e64 v26, v26, 22, s[48:49]
	v_cmp_gt_f32_e64 s[48:49], v39, v24
	s_nop 1
	v_cndmask_b32_e64 v24, v24, v39, s[48:49]
	v_cndmask_b32_e64 v26, v26, 23, s[48:49]
	v_cmp_gt_f32_e64 s[48:49], v48, v24
	s_nop 1
	v_cndmask_b32_e64 v24, v24, v48, s[48:49]
	v_cndmask_b32_e64 v26, v26, 24, s[48:49]
	v_cmp_gt_f32_e64 s[48:49], v49, v24
	s_nop 1
	v_cndmask_b32_e64 v24, v24, v49, s[48:49]
	v_cndmask_b32_e64 v26, v26, 25, s[48:49]
	v_cmp_gt_f32_e64 s[48:49], v50, v24
	s_nop 1
	v_cndmask_b32_e64 v24, v24, v50, s[48:49]
	v_cndmask_b32_e64 v26, v26, 26, s[48:49]
	v_cmp_gt_f32_e64 s[48:49], v51, v24
	s_nop 1
	v_cndmask_b32_e64 v24, v24, v51, s[48:49]
	v_cndmask_b32_e64 v26, v26, 27, s[48:49]
	v_cmp_gt_f32_e64 s[48:49], v52, v24
	s_nop 1
	v_cndmask_b32_e64 v24, v24, v52, s[48:49]
	v_cndmask_b32_e64 v26, v26, 28, s[48:49]
	v_cmp_gt_f32_e64 s[48:49], v53, v24
	s_nop 1
	v_cndmask_b32_e64 v24, v24, v53, s[48:49]
	v_cndmask_b32_e64 v26, v26, 29, s[48:49]
	v_cmp_gt_f32_e64 s[48:49], v55, v24
	s_nop 1
	v_cndmask_b32_e64 v33, v24, v55, s[48:49]
	v_cndmask_b32_e64 v26, v26, 30, s[48:49]
	v_cmp_gt_f32_e64 s[48:49], v35, v33
	s_nop 1
	v_cndmask_b32_e64 v24, v26, 31, s[48:49]
	v_lshl_add_u32 v26, v18, 2, 0
	ds_add_rtn_u32 v34, v26, v222 offset:16384
	v_lshl_add_u32 v26, v20, 2, 0
	ds_add_rtn_u32 v30, v26, v222 offset:16384
	v_lshl_add_u32 v26, v22, 2, 0
	ds_add_rtn_u32 v28, v26, v222 offset:16384
	v_lshl_add_u32 v26, v24, 2, 0
	ds_add_rtn_u32 v26, v26, v222 offset:16384
	s_waitcnt lgkmcnt(0)
	s_and_saveexec_b64 s[4:5], s[40:41]
	s_cbranch_execz .LBB0_2133
	ds_read_b32 v37, v157 offset:16384
	v_mov_b32_e32 v25, 0
	s_waitcnt lgkmcnt(0)
	v_cmp_lt_i32_e64 s[50:51], 0, v37
	s_and_saveexec_b64 s[6:7], s[50:51]
	s_cbranch_execz .LBB0_2132
	global_atomic_add v25, v[122:123], v37, off sc0
	s_branch .LBB0_2132
